# P6: epilogue row-sum loads issued before next-tile LDS-DMA prefetch, counted vmcnt(14) so prefetch lands under epilogue VALU
# baseline (speedup 1.0000x reference)
; template <class Epi>
; __device__ __forceinline__ void gemm_tile(const u16* __restrict__ A, const u16* __restrict__ Bt, int K,
;                                           int brow, int bcol, bool first, bool has_next, int nbrow, int nbcol, Epi epi) {
;     ...
;   if (has_next) {
;     STAGE(SB(0, 0), Bt, nbcol, 0); STAGE(SA(0, 0), A, nbrow, 0);
;     STAGE(SB(0, 1), Bt, nbcol + HALF, 0); STAGE(SA(0, 1), A, nbrow + HALF, 0);
;     STAGE(SB(1, 0), Bt, nbcol, 1); STAGE(SA(1, 0), A, nbrow, 1); STAGE(SB(1, 1), Bt, nbcol + HALF, 1);
;   }
;   __device__ __forceinline__ void operator()(f32x4 (&acc)[2][2][4][2], int brow, int bcol, int wr, int wc, int fr, int fq) const {
;     const float* ssq1 = (const float*)(p.ws + OFF_SSQ1);
;     u16* act = (u16*)(p.ws + OFF_ACT);
;     int t = bcol >> 8;
;     float sv[2][4][4];
; #pragma unroll
;     for (int ai = 0; ai < 2; ++ai)
; #pragma unroll
;       for (int m = 0; m < 4; ++m)
; #pragma unroll
;         for (int j = 0; j < 4; ++j) sv[ai][m][j] = ssq1[(size_t)(brow + ai * 128 + wr * 64 + m * 16 + fq * 4 + j) * 16 + fr];
;     __builtin_amdgcn_sched_barrier(0);
.LBB0_579:
	v_mov_b32_e32 v200, v128
	v_mov_b32_e32 v201, v129
	v_mov_b32_e32 v202, v130
	v_mov_b32_e32 v203, v131
	v_mov_b32_e32 v204, v149
	v_mov_b32_e32 v205, v150
	v_mov_b32_e32 v206, v151
	v_mov_b32_e32 v207, v152
	v_mov_b32_e32 v208, v153
	v_mov_b32_e32 v209, v154
	v_mov_b32_e32 v210, v165
	v_mov_b32_e32 v211, v166
	v_mov_b32_e32 v212, v167
	v_mov_b32_e32 v213, v168
	v_mov_b32_e32 v214, v169
	v_mov_b32_e32 v215, v170
	v_mov_b32_e32 v216, v171
	v_mov_b32_e32 v217, v172
	v_mbcnt_lo_u32_b32 v163, -1, 0
	v_mbcnt_hi_u32_b32 v163, -1, v163
	s_nop 0
	v_add_u32_e32 v178, s33, v163
	v_ashrrev_i32_e32 v130, 2, v178
	v_lshrrev_b32_e32 v131, 2, v163
	v_and_b32_e32 v130, 0xffffffc0, v130
	v_and_b32_e32 v131, 12, v131
	v_and_b32_e32 v128, 15, v163
	v_add3_u32 v132, v131, s2, v130
	v_lshlrev_b32_e32 v128, 2, v128
	v_ashrrev_i32_e32 v133, 31, v132
	v_add_u32_e32 v136, 16, v132
	v_add_u32_e32 v138, 17, v132
	v_add_u32_e32 v140, 18, v132
	v_add_u32_e32 v142, 19, v132
	v_lshl_add_u64 v[130:131], s[8:9], 0, v[128:129]
	v_lshlrev_b64 v[134:135], 6, v[132:133]
	v_ashrrev_i32_e32 v137, 31, v136
	v_ashrrev_i32_e32 v139, 31, v138
	v_ashrrev_i32_e32 v141, 31, v140
	v_ashrrev_i32_e32 v143, 31, v142
	v_lshl_add_u64 v[134:135], v[130:131], 0, v[134:135]
	v_lshlrev_b64 v[136:137], 6, v[136:137]
	v_lshlrev_b64 v[138:139], 6, v[138:139]
	v_lshlrev_b64 v[140:141], 6, v[140:141]
	v_lshlrev_b64 v[142:143], 6, v[142:143]
	v_lshl_add_u64 v[136:137], v[130:131], 0, v[136:137]
	v_lshl_add_u64 v[138:139], v[130:131], 0, v[138:139]
	v_lshl_add_u64 v[140:141], v[130:131], 0, v[140:141]
	v_lshl_add_u64 v[142:143], v[130:131], 0, v[142:143]
	global_load_dword v165, v[134:135], off
	global_load_dword v164, v[134:135], off offset:64
	global_load_dword v167, v[134:135], off offset:128
	global_load_dword v166, v[134:135], off offset:192
	global_load_dword v161, v[136:137], off
	global_load_dword v160, v[138:139], off
	global_load_dword v159, v[140:141], off
	global_load_dword v158, v[142:143], off
	v_add_u32_e32 v134, 32, v132
	v_add_u32_e32 v144, 49, v132
	v_ashrrev_i32_e32 v135, 31, v134
	v_add_u32_e32 v136, 33, v132
	v_add_u32_e32 v138, 34, v132
	v_add_u32_e32 v140, 35, v132
	v_add_u32_e32 v142, 48, v132
	v_ashrrev_i32_e32 v145, 31, v144
	v_add_u32_e32 v146, 50, v132
	v_add_u32_e32 v148, 51, v132
	v_lshlrev_b64 v[134:135], 6, v[134:135]
	v_ashrrev_i32_e32 v137, 31, v136
	v_ashrrev_i32_e32 v139, 31, v138
	v_ashrrev_i32_e32 v141, 31, v140
	v_ashrrev_i32_e32 v143, 31, v142
	v_lshlrev_b64 v[144:145], 6, v[144:145]
	v_ashrrev_i32_e32 v147, 31, v146
	v_ashrrev_i32_e32 v149, 31, v148
	v_lshl_add_u64 v[134:135], v[130:131], 0, v[134:135]
	v_lshlrev_b64 v[136:137], 6, v[136:137]
	v_lshlrev_b64 v[138:139], 6, v[138:139]
	v_lshlrev_b64 v[140:141], 6, v[140:141]
	v_lshlrev_b64 v[142:143], 6, v[142:143]
	v_lshl_add_u64 v[144:145], v[130:131], 0, v[144:145]
	v_lshlrev_b64 v[146:147], 6, v[146:147]
	v_lshlrev_b64 v[148:149], 6, v[148:149]
	v_lshl_add_u64 v[136:137], v[130:131], 0, v[136:137]
	v_lshl_add_u64 v[138:139], v[130:131], 0, v[138:139]
	v_lshl_add_u64 v[140:141], v[130:131], 0, v[140:141]
	v_lshl_add_u64 v[142:143], v[130:131], 0, v[142:143]
	v_lshl_add_u64 v[146:147], v[130:131], 0, v[146:147]
	v_lshl_add_u64 v[148:149], v[130:131], 0, v[148:149]
	global_load_dword v157, v[134:135], off
	global_load_dword v156, v[136:137], off
	global_load_dword v155, v[138:139], off
	global_load_dword v154, v[140:141], off
	global_load_dword v153, v[142:143], off
	global_load_dword v152, v[144:145], off
	global_load_dword v151, v[146:147], off
	global_load_dword v150, v[148:149], off
	v_add_u32_e32 v144, 0x91, v132
	v_ashrrev_i32_e32 v145, 31, v144
	v_lshlrev_b64 v[144:145], 6, v[144:145]
	v_lshl_add_u64 v[168:169], v[130:131], 0, v[144:145]
	v_add_u32_e32 v144, 0x92, v132
	v_ashrrev_i32_e32 v145, 31, v144
	v_add_u32_e32 v134, 0x80, v132
	v_add_u32_e32 v140, 0x83, v132
	v_add_u32_e32 v142, 0x90, v132
	v_lshlrev_b64 v[144:145], 6, v[144:145]
	v_ashrrev_i32_e32 v135, 31, v134
	v_add_u32_e32 v136, 0x81, v132
	v_add_u32_e32 v138, 0x82, v132
	v_ashrrev_i32_e32 v141, 31, v140
	v_ashrrev_i32_e32 v143, 31, v142
	v_lshl_add_u64 v[170:171], v[130:131], 0, v[144:145]
	v_add_u32_e32 v144, 0x93, v132
	v_lshlrev_b64 v[134:135], 6, v[134:135]
	v_ashrrev_i32_e32 v137, 31, v136
	v_ashrrev_i32_e32 v139, 31, v138
	v_lshlrev_b64 v[140:141], 6, v[140:141]
	v_lshlrev_b64 v[142:143], 6, v[142:143]
	v_ashrrev_i32_e32 v145, 31, v144
	v_lshl_add_u64 v[134:135], v[130:131], 0, v[134:135]
	v_lshlrev_b64 v[136:137], 6, v[136:137]
	v_lshlrev_b64 v[138:139], 6, v[138:139]
	v_lshl_add_u64 v[140:141], v[130:131], 0, v[140:141]
	v_lshl_add_u64 v[142:143], v[130:131], 0, v[142:143]
	v_lshlrev_b64 v[144:145], 6, v[144:145]
	v_lshl_add_u64 v[136:137], v[130:131], 0, v[136:137]
	v_lshl_add_u64 v[138:139], v[130:131], 0, v[138:139]
	v_lshl_add_u64 v[172:173], v[130:131], 0, v[144:145]
	global_load_dword v149, v[134:135], off
	global_load_dword v148, v[136:137], off
	global_load_dword v147, v[138:139], off
	global_load_dword v146, v[140:141], off
	global_load_dword v145, v[142:143], off
	global_load_dword v144, v[168:169], off
	s_nop 0
	global_load_dword v143, v[170:171], off
	global_load_dword v142, v[172:173], off
	v_add_u32_e32 v140, 0xa3, v132
	v_ashrrev_i32_e32 v141, 31, v140
	v_lshlrev_b64 v[140:141], 6, v[140:141]
	v_lshl_add_u64 v[168:169], v[130:131], 0, v[140:141]
	v_add_u32_e32 v140, 0xb0, v132
	v_ashrrev_i32_e32 v141, 31, v140
	v_lshlrev_b64 v[140:141], 6, v[140:141]
	v_lshl_add_u64 v[170:171], v[130:131], 0, v[140:141]
	v_add_u32_e32 v140, 0xb1, v132
	v_ashrrev_i32_e32 v141, 31, v140
	v_lshlrev_b64 v[140:141], 6, v[140:141]
	v_lshl_add_u64 v[172:173], v[130:131], 0, v[140:141]
	v_add_u32_e32 v140, 0xb2, v132
	v_ashrrev_i32_e32 v141, 31, v140
	v_add_u32_e32 v134, 0xa0, v132
	v_add_u32_e32 v136, 0xa1, v132
	v_add_u32_e32 v138, 0xa2, v132
	v_lshlrev_b64 v[140:141], 6, v[140:141]
	v_ashrrev_i32_e32 v135, 31, v134
	v_ashrrev_i32_e32 v137, 31, v136
	v_ashrrev_i32_e32 v139, 31, v138
	v_lshl_add_u64 v[174:175], v[130:131], 0, v[140:141]
	v_add_u32_e32 v140, 0xb3, v132
	v_lshlrev_b64 v[134:135], 6, v[134:135]
	v_lshlrev_b64 v[136:137], 6, v[136:137]
	v_lshlrev_b64 v[138:139], 6, v[138:139]
	v_ashrrev_i32_e32 v141, 31, v140
	v_lshl_add_u64 v[134:135], v[130:131], 0, v[134:135]
	v_lshl_add_u64 v[136:137], v[130:131], 0, v[136:137]
	v_lshl_add_u64 v[138:139], v[130:131], 0, v[138:139]
	v_lshlrev_b64 v[140:141], 6, v[140:141]
	v_lshl_add_u64 v[176:177], v[130:131], 0, v[140:141]
	global_load_dword v141, v[134:135], off
	global_load_dword v140, v[136:137], off
	s_nop 0
	global_load_dword v139, v[138:139], off
	s_nop 0
	global_load_dword v138, v[168:169], off
	global_load_dword v137, v[170:171], off
	global_load_dword v136, v[172:173], off
	global_load_dword v131, v[174:175], off
	global_load_dword v130, v[176:177], off
	s_andn2_b64 vcc, exec, s[4:5]
	s_cbranch_vccnz .Lmy_p6_nonext
; template <class Epi>
; __device__ __forceinline__ void gemm_tile(const u16* __restrict__ A, const u16* __restrict__ Bt, int K,
;                                           int brow, int bcol, bool first, bool has_next, int nbrow, int nbcol, Epi epi) {
;     ...
;   if (has_next) {
;     STAGE(SB(0, 0), Bt, nbcol, 0); STAGE(SA(0, 0), A, nbrow, 0);
;     STAGE(SB(0, 1), Bt, nbcol + HALF, 0); STAGE(SA(0, 1), A, nbrow + HALF, 0);
;     STAGE(SB(1, 0), Bt, nbcol, 1); STAGE(SA(1, 0), A, nbrow, 1); STAGE(SB(1, 1), Bt, nbcol + HALF, 1);
;   }
	s_ashr_i32 s29, s28, 31
	s_lshl_b64 s[4:5], s[28:29], 11
	s_add_u32 s4, s25, s4
	s_addc_u32 s5, s27, s5
	s_ashr_i32 s31, s30, 31
	v_lshl_add_u64 v[220:221], s[4:5], 0, v[200:201]
	v_lshl_add_u64 v[222:223], s[4:5], 0, v[202:203]
	s_lshl_b64 s[4:5], s[30:31], 11
	s_add_u32 s4, s6, s4
	s_addc_u32 s5, s7, s5
	v_lshl_add_u64 v[224:225], s[4:5], 0, v[200:201]
	v_lshl_add_u64 v[226:227], s[4:5], 0, v[202:203]
	s_or_b32 s4, s28, 0x80
	s_ashr_i32 s5, s4, 31
	s_lshl_b64 s[4:5], s[4:5], 11
	v_readfirstlane_b32 s1, v209
	s_add_u32 s4, s25, s4
	s_mov_b32 m0, s1
	v_readfirstlane_b32 s1, v210
	s_addc_u32 s5, s27, s5
	global_load_lds_dwordx4 v[220:221], off
	s_mov_b32 m0, s1
	v_readfirstlane_b32 s1, v208
	v_lshl_add_u64 v[228:229], s[4:5], 0, v[200:201]
	v_lshl_add_u64 v[230:231], s[4:5], 0, v[202:203]
	s_or_b32 s4, s30, 0x80
	global_load_lds_dwordx4 v[222:223], off
	s_mov_b32 m0, s1
	v_readfirstlane_b32 s1, v207
	s_ashr_i32 s5, s4, 31
	global_load_lds_dwordx4 v[224:225], off
	s_mov_b32 m0, s1
	v_readfirstlane_b32 s1, v206
	s_lshl_b64 s[4:5], s[4:5], 11
	global_load_lds_dwordx4 v[226:227], off
	s_mov_b32 m0, s1
	v_readfirstlane_b32 s1, v211
	s_add_u32 s4, s6, s4
	global_load_lds_dwordx4 v[228:229], off
	s_mov_b32 m0, s1
	s_addc_u32 s5, s7, s5
	v_readfirstlane_b32 s1, v205
	global_load_lds_dwordx4 v[230:231], off
	v_lshl_add_u64 v[232:233], s[4:5], 0, v[200:201]
	s_mov_b32 m0, s1
	v_readfirstlane_b32 s1, v204
	global_load_lds_dwordx4 v[232:233], off
	v_lshl_add_u64 v[202:203], s[4:5], 0, v[202:203]
	s_mov_b32 m0, s1
	v_readfirstlane_b32 s1, v212
	global_load_lds_dwordx4 v[202:203], off
	v_lshl_add_u64 v[202:203], v[220:221], 0, s[10:11]
	s_mov_b32 m0, s1
	v_readfirstlane_b32 s1, v213
	global_load_lds_dwordx4 v[202:203], off
	v_lshl_add_u64 v[202:203], v[222:223], 0, s[10:11]
	s_mov_b32 m0, s1
	v_readfirstlane_b32 s1, v214
	global_load_lds_dwordx4 v[202:203], off
	v_lshl_add_u64 v[202:203], v[224:225], 0, s[10:11]
	s_mov_b32 m0, s1
	v_readfirstlane_b32 s1, v215
	global_load_lds_dwordx4 v[202:203], off
	v_lshl_add_u64 v[202:203], v[226:227], 0, s[10:11]
	s_mov_b32 m0, s1
	v_readfirstlane_b32 s1, v216
	global_load_lds_dwordx4 v[202:203], off
	v_lshl_add_u64 v[202:203], v[228:229], 0, s[10:11]
	s_mov_b32 m0, s1
	v_readfirstlane_b32 s1, v217
	global_load_lds_dwordx4 v[202:203], off
	v_lshl_add_u64 v[202:203], v[230:231], 0, s[10:11]
	s_mov_b32 m0, s1
	s_nop 0
	global_load_lds_dwordx4 v[202:203], off
	s_waitcnt vmcnt(14)
	s_branch .Lmy_p6_go

; __device__ __forceinline__ float fast_silu(float z) { return z * __builtin_amdgcn_rcpf(1.f + __expf(-z)); }
;   __device__ __forceinline__ void operator()(f32x4 (&acc)[2][2][4][2], int brow, int bcol, int wr, int wc, int fr, int fq) const {
;     ...
; #pragma unroll
;     for (int ai = 0; ai < 2; ++ai)
; #pragma unroll
;       for (int m = 0; m < 4; ++m) {
;         int row0 = brow + ai * 128 + wr * 64 + m * 16 + fq * 4;
;         float rs[4];
; #pragma unroll
;         for (int j = 0; j < 4; ++j) rs[j] = rsqrtf(row16_sum(sv[ai][m][j]) * (1.f / 1024.f) + 1e-6f);
; #pragma unroll
;         for (int n = 0; n < 2; ++n) {
;           float a[4];
; #pragma unroll
;           for (int j = 0; j < 4; ++j) {
;             float g = acc[ai][0][m][n][j] * rs[j], u = acc[ai][1][m][n][j] * rs[j];
;             a[j] = fast_silu(g) * u;
;           }
;           store_rm4(act, 2816, row0, t * 128 + wc * 32 + n * 16 + fr, a[0], a[1], a[2], a[3], fr & 1);
;         }
.Lmy_p6_go:
	v_lshrrev_b32_e32 v128, 1, v178
	v_and_b32_e32 v169, 1, v163
	v_and_b32_e32 v168, 0x60, v128
	v_add_u32_e32 v128, v132, v169
	v_mov_b32_dpp v133, v165 row_ror:8 row_mask:0xf bank_mask:0xf bound_ctrl:1
	v_mov_b32_dpp v132, v164 row_ror:8 row_mask:0xf bank_mask:0xf bound_ctrl:1
	v_pk_add_f32 v[132:133], v[164:165], v[132:133]
	s_ashr_i32 s0, s0, 1
	s_and_b32 s2, s0, 0xffffff80
	v_mov_b32_dpp v135, v133 row_ror:4 row_mask:0xf bank_mask:0xf bound_ctrl:1
	v_mov_b32_dpp v134, v132 row_ror:4 row_mask:0xf bank_mask:0xf bound_ctrl:1
	v_pk_add_f32 v[132:133], v[132:133], v[134:135]
	v_and_b32_e32 v163, 14, v163
	v_mov_b32_e32 v174, v124
	v_mov_b32_dpp v135, v133 row_ror:2 row_mask:0xf bank_mask:0xf bound_ctrl:1
	v_mov_b32_dpp v134, v132 row_ror:2 row_mask:0xf bank_mask:0xf bound_ctrl:1
	v_pk_add_f32 v[132:133], v[132:133], v[134:135]
	v_mov_b32_e32 v175, v120
	v_add_u32_e32 v124, 2, v128
	v_mov_b32_dpp v135, v133 row_ror:1 row_mask:0xf bank_mask:0xf bound_ctrl:1
	v_mov_b32_dpp v134, v132 row_ror:1 row_mask:0xf bank_mask:0xf bound_ctrl:1
	v_pk_add_f32 v[134:135], v[132:133], v[134:135]
	v_mov_b64_e32 v[132:133], s[26:27]
	v_pk_fma_f32 v[134:135], v[134:135], s[24:25], v[132:133] op_sel_hi:[1,0,0]
	s_nop 0
	v_mul_f32_e32 v164, 0x4b800000, v135
	v_cmp_gt_f32_e32 vcc, s62, v135
	v_cmp_gt_f32_e64 s[0:1], s62, v134
	s_nop 0
	v_cndmask_b32_e32 v135, v135, v164, vcc
	v_rsq_f32_e32 v135, v135
	v_mul_f32_e32 v164, 0x4b800000, v134
	v_cndmask_b32_e64 v134, v134, v164, s[0:1]
	v_rsq_f32_e32 v165, v134
	v_mul_f32_e32 v134, 0x45800000, v135
	v_or3_b32 v164, v163, s2, v168
	v_cndmask_b32_e32 v168, v135, v134, vcc
	v_mov_b32_dpp v135, v167 row_ror:8 row_mask:0xf bank_mask:0xf bound_ctrl:1
	v_mov_b32_dpp v134, v166 row_ror:8 row_mask:0xf bank_mask:0xf bound_ctrl:1
	v_pk_add_f32 v[134:135], v[166:167], v[134:135]
	v_pk_mul_f32 v[174:175], v[174:175], v[168:169] op_sel_hi:[1,0]
	v_mul_f32_e32 v163, 0x45800000, v165
	v_mov_b32_dpp v167, v135 row_ror:4 row_mask:0xf bank_mask:0xf bound_ctrl:1
	v_mov_b32_dpp v166, v134 row_ror:4 row_mask:0xf bank_mask:0xf bound_ctrl:1
	v_pk_add_f32 v[134:135], v[134:135], v[166:167]
	v_mul_f32_e32 v120, 0xbfb8aa3b, v175
	v_exp_f32_e32 v120, v120
	v_mov_b32_dpp v167, v135 row_ror:2 row_mask:0xf bank_mask:0xf bound_ctrl:1
	v_mov_b32_dpp v166, v134 row_ror:2 row_mask:0xf bank_mask:0xf bound_ctrl:1
	v_pk_add_f32 v[134:135], v[134:135], v[166:167]
	v_add_f32_e32 v120, 1.0, v120
	s_nop 0
	v_mov_b32_dpp v167, v135 row_ror:1 row_mask:0xf bank_mask:0xf bound_ctrl:1
	v_mov_b32_dpp v166, v134 row_ror:1 row_mask:0xf bank_mask:0xf bound_ctrl:1
	v_pk_add_f32 v[134:135], v[134:135], v[166:167]
	s_nop 0
	v_pk_fma_f32 v[134:135], v[134:135], s[24:25], v[132:133] op_sel_hi:[1,0,0]
	s_nop 0
	v_mul_f32_e32 v166, 0x4b800000, v135
	v_cmp_gt_f32_e32 vcc, s62, v135
	v_cmp_gt_f32_e64 s[2:3], s62, v134
	s_nop 0
	v_cndmask_b32_e32 v135, v135, v166, vcc
	v_rsq_f32_e32 v135, v135
	v_mul_f32_e32 v166, 0x4b800000, v134
	v_cndmask_b32_e64 v134, v134, v166, s[2:3]
	v_cndmask_b32_e64 v166, v165, v163, s[0:1]
	v_mul_f32_e32 v163, 0x45800000, v135
	v_cndmask_b32_e32 v170, v135, v163, vcc
	v_rcp_f32_e32 v163, v120
	v_rsq_f32_e32 v134, v134
	v_mov_b32_e32 v120, v125
	v_pk_mul_f32 v[120:121], v[120:121], v[166:167] op_sel_hi:[1,0]
	v_mul_f32_e32 v163, v175, v163
	v_mul_f32_e32 v163, v174, v163
	v_mov_b32_e32 v174, v126
	v_mov_b32_e32 v175, v122
	v_pk_mul_f32 v[174:175], v[174:175], v[170:171] op_sel_hi:[1,0]
	v_mul_f32_e32 v135, 0x45800000, v134
	v_mul_f32_e32 v122, 0xbfb8aa3b, v175
	v_cndmask_b32_e64 v172, v134, v135, s[2:3]
	v_mul_f32_e32 v125, 0xbfb8aa3b, v121
	v_exp_f32_e32 v126, v122
	v_mov_b32_e32 v122, v127
	v_exp_f32_e32 v165, v125
	v_pk_mul_f32 v[122:123], v[122:123], v[172:173] op_sel_hi:[1,0]
	v_add_f32_e32 v126, 1.0, v126
	v_mul_f32_e32 v127, 0xbfb8aa3b, v123
	v_exp_f32_e32 v127, v127
	v_add_f32_e32 v165, 1.0, v165
	v_rcp_f32_e32 v165, v165
	v_rcp_f32_e32 v126, v126
	v_add_f32_e32 v127, 1.0, v127
	v_rcp_f32_e32 v127, v127
	v_mul_f32_e32 v121, v121, v165
	v_mul_f32_e32 v120, v120, v121
	v_mul_f32_e32 v121, v175, v126
	v_mul_f32_e32 v126, v174, v121
	v_mul_f32_e32 v121, v123, v127
	v_cmp_eq_u32_e32 vcc, 0, v169
	v_mul_f32_e32 v167, v122, v121
	v_mov_b64_e32 v[134:135], s[34:35]
	v_cndmask_b32_e32 v121, v163, v120, vcc
	v_ashrrev_i32_e32 v165, 31, v164
	v_mad_i64_i32 v[176:177], s[0:1], v128, s63, v[134:135]
	v_mov_b32_dpp v121, v121 quad_perm:[1,0,3,2] row_mask:0xf bank_mask:0xf bound_ctrl:1
	v_cndmask_b32_e32 v122, v121, v163, vcc
	v_cndmask_b32_e32 v120, v120, v121, vcc
	v_cvt_pk_bf16_f32 v127, v122, v120
	v_lshlrev_b64 v[120:121], 1, v[164:165]
	v_lshl_add_u64 v[122:123], v[176:177], 0, v[120:121]
	global_store_dword v[122:123], v127, off
	v_cndmask_b32_e32 v127, v126, v167, vcc
	v_mad_i64_i32 v[124:125], s[0:1], v124, s63, v[134:135]
	s_nop 0
	v_mov_b32_dpp v163, v127 quad_perm:[1,0,3,2] row_mask:0xf bank_mask:0xf bound_ctrl:1
	v_cndmask_b32_e32 v164, v163, v126, vcc
	v_mov_b32_e32 v126, v116
	v_mov_b32_e32 v127, v112
	v_pk_mul_f32 v[126:127], v[126:127], v[168:169] op_sel_hi:[1,0]
	v_cndmask_b32_e32 v116, v167, v163, vcc
	v_mul_f32_e32 v112, 0xbfb8aa3b, v127
	v_exp_f32_e32 v112, v112
	v_cvt_pk_bf16_f32 v116, v164, v116
	v_lshl_add_u64 v[124:125], v[124:125], 0, v[120:121]
	global_store_dword v[124:125], v116, off
	v_add_f32_e32 v112, 1.0, v112
	v_rcp_f32_e32 v163, v112
	v_mov_b32_e32 v112, v117
	v_pk_mul_f32 v[112:113], v[112:113], v[166:167] op_sel_hi:[1,0]
	v_mul_f32_e32 v116, v127, v163
	v_mul_f32_e32 v117, 0xbfb8aa3b, v113
	v_exp_f32_e32 v117, v117
	v_mul_f32_e32 v126, v126, v116
	v_add_f32_e32 v116, 1.0, v117
	v_rcp_f32_e32 v127, v116
; __device__ __forceinline__ float fast_silu(float z) { return z * __builtin_amdgcn_rcpf(1.f + __expf(-z)); }
;   __device__ __forceinline__ void operator()(f32x4 (&acc)[2][2][4][2], int brow, int bcol, int wr, int wc, int fr, int fq) const {
;     ...
; #pragma unroll
;     for (int ai = 0; ai < 2; ++ai)
; #pragma unroll
;       for (int m = 0; m < 4; ++m) {
;         int row0 = brow + ai * 128 + wr * 64 + m * 16 + fq * 4;
;         float rs[4];
; #pragma unroll
;         for (int j = 0; j < 4; ++j) rs[j] = rsqrtf(row16_sum(sv[ai][m][j]) * (1.f / 1024.f) + 1e-6f);
; #pragma unroll
;         for (int n = 0; n < 2; ++n) {
;           float a[4];
; #pragma unroll
;           for (int j = 0; j < 4; ++j) {
;             float g = acc[ai][0][m][n][j] * rs[j], u = acc[ai][1][m][n][j] * rs[j];
;             a[j] = fast_silu(g) * u;
;           }
;           store_rm4(act, 2816, row0, t * 128 + wc * 32 + n * 16 + fr, a[0], a[1], a[2], a[3], fr & 1);
;         }
;         __builtin_amdgcn_sched_barrier(0);
;       }
	v_mov_b32_e32 v116, v118
	v_mov_b32_e32 v117, v114
	v_pk_mul_f32 v[116:117], v[116:117], v[170:171] op_sel_hi:[1,0]
	v_mul_f32_e32 v113, v113, v127
	v_mul_f32_e32 v114, 0xbfb8aa3b, v117
	v_exp_f32_e32 v118, v114
	v_mov_b32_e32 v114, v119
	v_pk_mul_f32 v[114:115], v[114:115], v[172:173] op_sel_hi:[1,0]
	v_mul_f32_e32 v112, v112, v113
	v_mul_f32_e32 v119, 0xbfb8aa3b, v115
	v_exp_f32_e32 v119, v119
	v_add_f32_e32 v118, 1.0, v118
	v_rcp_f32_e32 v118, v118
	v_add_f32_e32 v119, 1.0, v119
	v_rcp_f32_e32 v119, v119
	v_mul_f32_e32 v113, v117, v118
	v_mul_f32_e32 v113, v116, v113
	v_mul_f32_e32 v115, v115, v119
	v_mul_f32_e32 v114, v114, v115
	v_cndmask_b32_e32 v115, v126, v112, vcc
	s_nop 1
	v_mov_b32_dpp v115, v115 quad_perm:[1,0,3,2] row_mask:0xf bank_mask:0xf bound_ctrl:1
	v_cndmask_b32_e32 v116, v115, v126, vcc
	v_cndmask_b32_e32 v112, v112, v115, vcc
	v_cvt_pk_bf16_f32 v112, v116, v112
	global_store_dword v[122:123], v112, off offset:32
	v_cndmask_b32_e32 v112, v113, v114, vcc
	s_nop 1
	v_mov_b32_dpp v112, v112 quad_perm:[1,0,3,2] row_mask:0xf bank_mask:0xf bound_ctrl:1
	v_cndmask_b32_e32 v113, v112, v113, vcc
	v_cndmask_b32_e32 v112, v114, v112, vcc
	v_cvt_pk_bf16_f32 v112, v113, v112
	global_store_dword v[124:125], v112, off offset:32
	v_mov_b32_dpp v113, v161 row_ror:8 row_mask:0xf bank_mask:0xf bound_ctrl:1
	v_mov_b32_dpp v112, v160 row_ror:8 row_mask:0xf bank_mask:0xf bound_ctrl:1
	v_pk_add_f32 v[112:113], v[160:161], v[112:113]
	v_mov_b32_e32 v122, v108
	v_mov_b32_e32 v123, v104
	v_mov_b32_dpp v115, v113 row_ror:4 row_mask:0xf bank_mask:0xf bound_ctrl:1
	v_mov_b32_dpp v114, v112 row_ror:4 row_mask:0xf bank_mask:0xf bound_ctrl:1
	v_pk_add_f32 v[112:113], v[112:113], v[114:115]
	v_add_u32_e32 v108, 18, v128
	s_nop 0
	v_mov_b32_dpp v115, v113 row_ror:2 row_mask:0xf bank_mask:0xf bound_ctrl:1
	v_mov_b32_dpp v114, v112 row_ror:2 row_mask:0xf bank_mask:0xf bound_ctrl:1
	v_pk_add_f32 v[112:113], v[112:113], v[114:115]
	s_nop 1
	v_mov_b32_dpp v115, v113 row_ror:1 row_mask:0xf bank_mask:0xf bound_ctrl:1
	v_mov_b32_dpp v114, v112 row_ror:1 row_mask:0xf bank_mask:0xf bound_ctrl:1
	v_pk_add_f32 v[112:113], v[112:113], v[114:115]
	v_mov_b32_dpp v115, v159 row_ror:8 row_mask:0xf bank_mask:0xf bound_ctrl:1
	v_pk_fma_f32 v[112:113], v[112:113], s[24:25], v[132:133] op_sel_hi:[1,0,0]
	s_nop 0
	v_mul_f32_e32 v114, 0x4b800000, v113
	v_cmp_gt_f32_e64 s[0:1], s62, v113
	v_cmp_gt_f32_e64 s[2:3], s62, v112
	s_nop 0
	v_cndmask_b32_e64 v113, v113, v114, s[0:1]
	v_mul_f32_e32 v114, 0x4b800000, v112
	v_cndmask_b32_e64 v112, v112, v114, s[2:3]
	v_rsq_f32_e32 v113, v113
	v_mov_b32_dpp v114, v158 row_ror:8 row_mask:0xf bank_mask:0xf bound_ctrl:1
	v_pk_add_f32 v[114:115], v[158:159], v[114:115]
	v_rsq_f32_e32 v118, v112
	v_mul_f32_e32 v112, 0x45800000, v113
	v_mov_b32_dpp v117, v115 row_ror:4 row_mask:0xf bank_mask:0xf bound_ctrl:1
	v_mov_b32_dpp v116, v114 row_ror:4 row_mask:0xf bank_mask:0xf bound_ctrl:1
	v_pk_add_f32 v[114:115], v[114:115], v[116:117]
	v_cndmask_b32_e64 v112, v113, v112, s[0:1]
	v_mul_f32_e32 v113, 0x45800000, v118
	v_mov_b32_dpp v117, v115 row_ror:2 row_mask:0xf bank_mask:0xf bound_ctrl:1
	v_mov_b32_dpp v116, v114 row_ror:2 row_mask:0xf bank_mask:0xf bound_ctrl:1
	v_pk_add_f32 v[114:115], v[114:115], v[116:117]
	s_nop 1
	v_mov_b32_dpp v117, v115 row_ror:1 row_mask:0xf bank_mask:0xf bound_ctrl:1
	v_mov_b32_dpp v116, v114 row_ror:1 row_mask:0xf bank_mask:0xf bound_ctrl:1
	v_pk_add_f32 v[114:115], v[114:115], v[116:117]
	s_nop 0
	v_pk_fma_f32 v[114:115], v[114:115], s[24:25], v[132:133] op_sel_hi:[1,0,0]
	s_nop 0
	v_mul_f32_e32 v116, 0x4b800000, v115
	v_cmp_gt_f32_e64 s[0:1], s62, v115
	v_cmp_gt_f32_e64 s[4:5], s62, v114
	s_nop 0
	v_cndmask_b32_e64 v115, v115, v116, s[0:1]
	v_mul_f32_e32 v116, 0x4b800000, v114
	v_rsq_f32_e32 v115, v115
	v_cndmask_b32_e64 v114, v114, v116, s[4:5]
	v_rsq_f32_e32 v117, v114
	v_cndmask_b32_e64 v114, v118, v113, s[2:3]
	v_mul_f32_e32 v113, 0x45800000, v115
	v_cndmask_b32_e64 v116, v115, v113, s[0:1]
	v_mul_f32_e32 v113, 0x45800000, v117
	v_cndmask_b32_e64 v118, v117, v113, s[4:5]
	v_add_u32_e32 v113, 16, v128
	v_pk_mul_f32 v[122:123], v[122:123], v[112:113] op_sel_hi:[1,0]
	v_mad_i64_i32 v[124:125], s[0:1], v113, s63, v[134:135]
	v_mul_f32_e32 v104, 0xbfb8aa3b, v123
	v_exp_f32_e32 v104, v104
	s_nop 0
	v_add_f32_e32 v104, 1.0, v104
	v_rcp_f32_e32 v113, v104
	v_mov_b32_e32 v104, v109
	v_pk_mul_f32 v[104:105], v[104:105], v[114:115] op_sel_hi:[1,0]
	v_mul_f32_e32 v113, v123, v113
	v_mul_f32_e32 v113, v122, v113
	v_mov_b32_e32 v122, v110
	v_mov_b32_e32 v123, v106
	v_pk_mul_f32 v[122:123], v[122:123], v[116:117] op_sel_hi:[1,0]
	v_mul_f32_e32 v109, 0xbfb8aa3b, v105
	v_mul_f32_e32 v106, 0xbfb8aa3b, v123
	v_exp_f32_e32 v110, v106
	v_mov_b32_e32 v106, v111
	v_exp_f32_e32 v115, v109
	v_pk_mul_f32 v[106:107], v[106:107], v[118:119] op_sel_hi:[1,0]
	v_add_f32_e32 v110, 1.0, v110
	v_mul_f32_e32 v111, 0xbfb8aa3b, v107
	v_exp_f32_e32 v111, v111
	v_add_f32_e32 v115, 1.0, v115
	v_rcp_f32_e32 v115, v115
	v_rcp_f32_e32 v110, v110
	v_add_f32_e32 v111, 1.0, v111
	v_rcp_f32_e32 v111, v111
	v_mul_f32_e32 v105, v105, v115
	v_mul_f32_e32 v104, v104, v105
	v_mul_f32_e32 v105, v123, v110
	v_mul_f32_e32 v110, v122, v105
	v_mul_f32_e32 v105, v107, v111
	v_mul_f32_e32 v111, v106, v105
	v_cndmask_b32_e32 v105, v113, v104, vcc
	v_mov_b32_e32 v107, v96
	v_mad_i64_i32 v[108:109], s[0:1], v108, s63, v[134:135]
	v_mov_b32_dpp v105, v105 quad_perm:[1,0,3,2] row_mask:0xf bank_mask:0xf bound_ctrl:1
	v_cndmask_b32_e32 v106, v105, v113, vcc
	v_cndmask_b32_e32 v104, v104, v105, vcc
	v_cvt_pk_bf16_f32 v106, v106, v104
	v_lshl_add_u64 v[104:105], v[124:125], 0, v[120:121]
; __device__ __forceinline__ float fast_silu(float z) { return z * __builtin_amdgcn_rcpf(1.f + __expf(-z)); }
;   __device__ __forceinline__ void operator()(f32x4 (&acc)[2][2][4][2], int brow, int bcol, int wr, int wc, int fr, int fq) const {
;     ...
; #pragma unroll
;     for (int ai = 0; ai < 2; ++ai)
; #pragma unroll
;       for (int m = 0; m < 4; ++m) {
;         int row0 = brow + ai * 128 + wr * 64 + m * 16 + fq * 4;
;         float rs[4];
; #pragma unroll
;         for (int j = 0; j < 4; ++j) rs[j] = rsqrtf(row16_sum(sv[ai][m][j]) * (1.f / 1024.f) + 1e-6f);
; #pragma unroll
;         for (int n = 0; n < 2; ++n) {
;           float a[4];
; #pragma unroll
;           for (int j = 0; j < 4; ++j) {
;             float g = acc[ai][0][m][n][j] * rs[j], u = acc[ai][1][m][n][j] * rs[j];
;             a[j] = fast_silu(g) * u;
;           }
;           store_rm4(act, 2816, row0, t * 128 + wc * 32 + n * 16 + fr, a[0], a[1], a[2], a[3], fr & 1);
;         }
;         __builtin_amdgcn_sched_barrier(0);
;       }
	global_store_dword v[104:105], v106, off
	v_cndmask_b32_e32 v106, v110, v111, vcc
	v_lshl_add_u64 v[108:109], v[108:109], 0, v[120:121]
	s_nop 0
	v_mov_b32_dpp v113, v106 quad_perm:[1,0,3,2] row_mask:0xf bank_mask:0xf bound_ctrl:1
	v_mov_b32_e32 v106, v100
	v_pk_mul_f32 v[106:107], v[106:107], v[112:113] op_sel_hi:[1,0]
	v_cndmask_b32_e32 v110, v113, v110, vcc
	v_mul_f32_e32 v96, 0xbfb8aa3b, v107
	v_exp_f32_e32 v96, v96
	v_cndmask_b32_e32 v100, v111, v113, vcc
	v_cvt_pk_bf16_f32 v100, v110, v100
	global_store_dword v[108:109], v100, off
	v_add_f32_e32 v96, 1.0, v96
	v_rcp_f32_e32 v110, v96
	v_mov_b32_e32 v96, v101
	v_pk_mul_f32 v[96:97], v[96:97], v[114:115] op_sel_hi:[1,0]
	v_mul_f32_e32 v100, v107, v110
	v_mul_f32_e32 v101, 0xbfb8aa3b, v97
	v_exp_f32_e32 v101, v101
	v_mul_f32_e32 v106, v106, v100
	v_add_f32_e32 v100, 1.0, v101
	v_rcp_f32_e32 v107, v100
	v_mov_b32_e32 v100, v102
	v_mov_b32_e32 v101, v98
	v_pk_mul_f32 v[100:101], v[100:101], v[116:117] op_sel_hi:[1,0]
	v_mul_f32_e32 v97, v97, v107
	v_mul_f32_e32 v98, 0xbfb8aa3b, v101
	v_exp_f32_e32 v102, v98
	v_mov_b32_e32 v98, v103
	v_pk_mul_f32 v[98:99], v[98:99], v[118:119] op_sel_hi:[1,0]
	v_mul_f32_e32 v96, v96, v97
	v_mul_f32_e32 v103, 0xbfb8aa3b, v99
	v_exp_f32_e32 v103, v103
	v_add_f32_e32 v102, 1.0, v102
	v_rcp_f32_e32 v102, v102
	v_add_f32_e32 v103, 1.0, v103
	v_rcp_f32_e32 v103, v103
	v_mul_f32_e32 v97, v101, v102
	v_mul_f32_e32 v97, v100, v97
	v_mul_f32_e32 v99, v99, v103
	v_mul_f32_e32 v98, v98, v99
	v_cndmask_b32_e32 v99, v106, v96, vcc
	s_nop 1
	v_mov_b32_dpp v99, v99 quad_perm:[1,0,3,2] row_mask:0xf bank_mask:0xf bound_ctrl:1
	v_cndmask_b32_e32 v100, v99, v106, vcc
	v_cndmask_b32_e32 v96, v96, v99, vcc
	v_cvt_pk_bf16_f32 v96, v100, v96
	global_store_dword v[104:105], v96, off offset:32
	v_cndmask_b32_e32 v96, v97, v98, vcc
	s_nop 1
	v_mov_b32_dpp v96, v96 quad_perm:[1,0,3,2] row_mask:0xf bank_mask:0xf bound_ctrl:1
	v_cndmask_b32_e32 v97, v96, v97, vcc
	v_cndmask_b32_e32 v96, v98, v96, vcc
	v_cvt_pk_bf16_f32 v96, v97, v96
	global_store_dword v[108:109], v96, off offset:32
	v_mov_b32_dpp v97, v157 row_ror:8 row_mask:0xf bank_mask:0xf bound_ctrl:1
	v_mov_b32_dpp v96, v156 row_ror:8 row_mask:0xf bank_mask:0xf bound_ctrl:1
	v_pk_add_f32 v[96:97], v[156:157], v[96:97]
	v_mov_b32_e32 v104, v92
	v_mov_b32_e32 v105, v88
	v_mov_b32_dpp v99, v97 row_ror:4 row_mask:0xf bank_mask:0xf bound_ctrl:1
	v_mov_b32_dpp v98, v96 row_ror:4 row_mask:0xf bank_mask:0xf bound_ctrl:1
	v_pk_add_f32 v[96:97], v[96:97], v[98:99]
	v_add_u32_e32 v92, 34, v128
	s_nop 0
	v_mov_b32_dpp v99, v97 row_ror:2 row_mask:0xf bank_mask:0xf bound_ctrl:1
	v_mov_b32_dpp v98, v96 row_ror:2 row_mask:0xf bank_mask:0xf bound_ctrl:1
	v_pk_add_f32 v[96:97], v[96:97], v[98:99]
	s_nop 1
	v_mov_b32_dpp v99, v97 row_ror:1 row_mask:0xf bank_mask:0xf bound_ctrl:1
	v_mov_b32_dpp v98, v96 row_ror:1 row_mask:0xf bank_mask:0xf bound_ctrl:1
	v_pk_add_f32 v[96:97], v[96:97], v[98:99]
	v_mov_b32_dpp v99, v155 row_ror:8 row_mask:0xf bank_mask:0xf bound_ctrl:1
	v_pk_fma_f32 v[96:97], v[96:97], s[24:25], v[132:133] op_sel_hi:[1,0,0]
	s_nop 0
	v_mul_f32_e32 v98, 0x4b800000, v97
	v_cmp_gt_f32_e64 s[0:1], s62, v97
	v_cmp_gt_f32_e64 s[2:3], s62, v96
	s_nop 0
	v_cndmask_b32_e64 v97, v97, v98, s[0:1]
	v_mul_f32_e32 v98, 0x4b800000, v96
	v_cndmask_b32_e64 v96, v96, v98, s[2:3]
	v_rsq_f32_e32 v97, v97
	v_mov_b32_dpp v98, v154 row_ror:8 row_mask:0xf bank_mask:0xf bound_ctrl:1
	v_pk_add_f32 v[98:99], v[154:155], v[98:99]
	v_rsq_f32_e32 v102, v96
	v_mul_f32_e32 v96, 0x45800000, v97
	v_mov_b32_dpp v101, v99 row_ror:4 row_mask:0xf bank_mask:0xf bound_ctrl:1
	v_mov_b32_dpp v100, v98 row_ror:4 row_mask:0xf bank_mask:0xf bound_ctrl:1
	v_pk_add_f32 v[98:99], v[98:99], v[100:101]
	v_cndmask_b32_e64 v96, v97, v96, s[0:1]
	v_mul_f32_e32 v97, 0x45800000, v102
	v_mov_b32_dpp v101, v99 row_ror:2 row_mask:0xf bank_mask:0xf bound_ctrl:1
	v_mov_b32_dpp v100, v98 row_ror:2 row_mask:0xf bank_mask:0xf bound_ctrl:1
	v_pk_add_f32 v[98:99], v[98:99], v[100:101]
	s_nop 1
	v_mov_b32_dpp v101, v99 row_ror:1 row_mask:0xf bank_mask:0xf bound_ctrl:1
	v_mov_b32_dpp v100, v98 row_ror:1 row_mask:0xf bank_mask:0xf bound_ctrl:1
	v_pk_add_f32 v[98:99], v[98:99], v[100:101]
	s_nop 0
	v_pk_fma_f32 v[98:99], v[98:99], s[24:25], v[132:133] op_sel_hi:[1,0,0]
	s_nop 0
	v_mul_f32_e32 v100, 0x4b800000, v99
	v_cmp_gt_f32_e64 s[0:1], s62, v99
	v_cmp_gt_f32_e64 s[4:5], s62, v98
	s_nop 0
	v_cndmask_b32_e64 v99, v99, v100, s[0:1]
	v_mul_f32_e32 v100, 0x4b800000, v98
	v_rsq_f32_e32 v99, v99
	v_cndmask_b32_e64 v98, v98, v100, s[4:5]
	v_rsq_f32_e32 v101, v98
	v_cndmask_b32_e64 v98, v102, v97, s[2:3]
	v_mul_f32_e32 v97, 0x45800000, v99
	v_cndmask_b32_e64 v100, v99, v97, s[0:1]
	v_mul_f32_e32 v97, 0x45800000, v101
	v_cndmask_b32_e64 v102, v101, v97, s[4:5]
	v_add_u32_e32 v97, 32, v128
	v_pk_mul_f32 v[104:105], v[104:105], v[96:97] op_sel_hi:[1,0]
	v_mad_i64_i32 v[106:107], s[0:1], v97, s63, v[134:135]
	v_mul_f32_e32 v88, 0xbfb8aa3b, v105
	v_exp_f32_e32 v88, v88
	s_nop 0
	v_add_f32_e32 v88, 1.0, v88
	v_rcp_f32_e32 v97, v88
	v_mov_b32_e32 v88, v93
	v_pk_mul_f32 v[88:89], v[88:89], v[98:99] op_sel_hi:[1,0]
	v_mul_f32_e32 v97, v105, v97
	v_mul_f32_e32 v97, v104, v97
	v_mov_b32_e32 v104, v94
	v_mov_b32_e32 v105, v90
	v_pk_mul_f32 v[104:105], v[104:105], v[100:101] op_sel_hi:[1,0]
	v_mul_f32_e32 v93, 0xbfb8aa3b, v89
	v_mul_f32_e32 v90, 0xbfb8aa3b, v105
	v_exp_f32_e32 v94, v90
	v_mov_b32_e32 v90, v95
	v_exp_f32_e32 v99, v93
	v_pk_mul_f32 v[90:91], v[90:91], v[102:103] op_sel_hi:[1,0]
	v_add_f32_e32 v94, 1.0, v94
	v_mul_f32_e32 v95, 0xbfb8aa3b, v91
	v_exp_f32_e32 v95, v95
	v_add_f32_e32 v99, 1.0, v99
; __device__ __forceinline__ float fast_silu(float z) { return z * __builtin_amdgcn_rcpf(1.f + __expf(-z)); }
;   __device__ __forceinline__ void operator()(f32x4 (&acc)[2][2][4][2], int brow, int bcol, int wr, int wc, int fr, int fq) const {
;     ...
; #pragma unroll
;     for (int ai = 0; ai < 2; ++ai)
; #pragma unroll
;       for (int m = 0; m < 4; ++m) {
;         int row0 = brow + ai * 128 + wr * 64 + m * 16 + fq * 4;
;         float rs[4];
; #pragma unroll
;         for (int j = 0; j < 4; ++j) rs[j] = rsqrtf(row16_sum(sv[ai][m][j]) * (1.f / 1024.f) + 1e-6f);
; #pragma unroll
;         for (int n = 0; n < 2; ++n) {
;           float a[4];
; #pragma unroll
;           for (int j = 0; j < 4; ++j) {
;             float g = acc[ai][0][m][n][j] * rs[j], u = acc[ai][1][m][n][j] * rs[j];
;             a[j] = fast_silu(g) * u;
;           }
;           store_rm4(act, 2816, row0, t * 128 + wc * 32 + n * 16 + fr, a[0], a[1], a[2], a[3], fr & 1);
;         }
;         __builtin_amdgcn_sched_barrier(0);
;       }
	v_rcp_f32_e32 v99, v99
	v_rcp_f32_e32 v94, v94
	v_add_f32_e32 v95, 1.0, v95
	v_rcp_f32_e32 v95, v95
	v_mul_f32_e32 v89, v89, v99
	v_mul_f32_e32 v88, v88, v89
	v_mul_f32_e32 v89, v105, v94
	v_mul_f32_e32 v94, v104, v89
	v_mul_f32_e32 v89, v91, v95
	v_mul_f32_e32 v95, v90, v89
	v_cndmask_b32_e32 v89, v97, v88, vcc
	v_mov_b32_e32 v91, v80
	v_mad_i64_i32 v[92:93], s[0:1], v92, s63, v[134:135]
	v_mov_b32_dpp v89, v89 quad_perm:[1,0,3,2] row_mask:0xf bank_mask:0xf bound_ctrl:1
	v_cndmask_b32_e32 v90, v89, v97, vcc
	v_cndmask_b32_e32 v88, v88, v89, vcc
	v_cvt_pk_bf16_f32 v90, v90, v88
	v_lshl_add_u64 v[88:89], v[106:107], 0, v[120:121]
	global_store_dword v[88:89], v90, off
	v_cndmask_b32_e32 v90, v94, v95, vcc
	v_lshl_add_u64 v[92:93], v[92:93], 0, v[120:121]
	s_nop 0
	v_mov_b32_dpp v97, v90 quad_perm:[1,0,3,2] row_mask:0xf bank_mask:0xf bound_ctrl:1
	v_mov_b32_e32 v90, v84
	v_pk_mul_f32 v[90:91], v[90:91], v[96:97] op_sel_hi:[1,0]
	v_cndmask_b32_e32 v94, v97, v94, vcc
	v_mul_f32_e32 v80, 0xbfb8aa3b, v91
	v_exp_f32_e32 v80, v80
	v_cndmask_b32_e32 v84, v95, v97, vcc
	v_cvt_pk_bf16_f32 v84, v94, v84
	global_store_dword v[92:93], v84, off
	v_add_f32_e32 v80, 1.0, v80
	v_rcp_f32_e32 v94, v80
	v_mov_b32_e32 v80, v85
	v_pk_mul_f32 v[80:81], v[80:81], v[98:99] op_sel_hi:[1,0]
	v_mul_f32_e32 v84, v91, v94
	v_mul_f32_e32 v85, 0xbfb8aa3b, v81
	v_exp_f32_e32 v85, v85
	v_mul_f32_e32 v90, v90, v84
	v_add_f32_e32 v84, 1.0, v85
	v_rcp_f32_e32 v91, v84
	v_mov_b32_e32 v84, v86
	v_mov_b32_e32 v85, v82
	v_pk_mul_f32 v[84:85], v[84:85], v[100:101] op_sel_hi:[1,0]
	v_mul_f32_e32 v81, v81, v91
	v_mul_f32_e32 v82, 0xbfb8aa3b, v85
	v_exp_f32_e32 v86, v82
	v_mov_b32_e32 v82, v87
	v_pk_mul_f32 v[82:83], v[82:83], v[102:103] op_sel_hi:[1,0]
	v_mul_f32_e32 v80, v80, v81
	v_mul_f32_e32 v87, 0xbfb8aa3b, v83
	v_exp_f32_e32 v87, v87
	v_add_f32_e32 v86, 1.0, v86
	v_rcp_f32_e32 v86, v86
	v_add_f32_e32 v87, 1.0, v87
	v_rcp_f32_e32 v87, v87
	v_mul_f32_e32 v81, v85, v86
	v_mul_f32_e32 v81, v84, v81
	v_mul_f32_e32 v83, v83, v87
	v_mul_f32_e32 v82, v82, v83
	v_cndmask_b32_e32 v83, v90, v80, vcc
	s_nop 1
	v_mov_b32_dpp v83, v83 quad_perm:[1,0,3,2] row_mask:0xf bank_mask:0xf bound_ctrl:1
	v_cndmask_b32_e32 v84, v83, v90, vcc
	v_cndmask_b32_e32 v80, v80, v83, vcc
	v_cvt_pk_bf16_f32 v80, v84, v80
	global_store_dword v[88:89], v80, off offset:32
	v_cndmask_b32_e32 v80, v81, v82, vcc
	s_nop 1
	v_mov_b32_dpp v80, v80 quad_perm:[1,0,3,2] row_mask:0xf bank_mask:0xf bound_ctrl:1
	v_cndmask_b32_e32 v81, v80, v81, vcc
	v_cndmask_b32_e32 v80, v82, v80, vcc
	v_cvt_pk_bf16_f32 v80, v81, v80
	global_store_dword v[92:93], v80, off offset:32
	v_mov_b32_dpp v81, v153 row_ror:8 row_mask:0xf bank_mask:0xf bound_ctrl:1
	v_mov_b32_dpp v80, v152 row_ror:8 row_mask:0xf bank_mask:0xf bound_ctrl:1
	v_pk_add_f32 v[80:81], v[152:153], v[80:81]
	v_mov_b32_e32 v88, v76
	v_mov_b32_e32 v89, v72
	v_mov_b32_dpp v83, v81 row_ror:4 row_mask:0xf bank_mask:0xf bound_ctrl:1
	v_mov_b32_dpp v82, v80 row_ror:4 row_mask:0xf bank_mask:0xf bound_ctrl:1
	v_pk_add_f32 v[80:81], v[80:81], v[82:83]
	v_add_u32_e32 v76, 50, v128
	s_nop 0
	v_mov_b32_dpp v83, v81 row_ror:2 row_mask:0xf bank_mask:0xf bound_ctrl:1
	v_mov_b32_dpp v82, v80 row_ror:2 row_mask:0xf bank_mask:0xf bound_ctrl:1
	v_pk_add_f32 v[80:81], v[80:81], v[82:83]
	s_nop 1
	v_mov_b32_dpp v83, v81 row_ror:1 row_mask:0xf bank_mask:0xf bound_ctrl:1
	v_mov_b32_dpp v82, v80 row_ror:1 row_mask:0xf bank_mask:0xf bound_ctrl:1
	v_pk_add_f32 v[80:81], v[80:81], v[82:83]
	v_mov_b32_dpp v83, v151 row_ror:8 row_mask:0xf bank_mask:0xf bound_ctrl:1
	v_pk_fma_f32 v[80:81], v[80:81], s[24:25], v[132:133] op_sel_hi:[1,0,0]
	s_nop 0
	v_mul_f32_e32 v82, 0x4b800000, v81
	v_cmp_gt_f32_e64 s[0:1], s62, v81
	v_cmp_gt_f32_e64 s[2:3], s62, v80
	s_nop 0
	v_cndmask_b32_e64 v81, v81, v82, s[0:1]
	v_mul_f32_e32 v82, 0x4b800000, v80
	v_cndmask_b32_e64 v80, v80, v82, s[2:3]
	v_rsq_f32_e32 v81, v81
	v_mov_b32_dpp v82, v150 row_ror:8 row_mask:0xf bank_mask:0xf bound_ctrl:1
	v_pk_add_f32 v[82:83], v[150:151], v[82:83]
	v_rsq_f32_e32 v86, v80
	v_mul_f32_e32 v80, 0x45800000, v81
	v_mov_b32_dpp v85, v83 row_ror:4 row_mask:0xf bank_mask:0xf bound_ctrl:1
	v_mov_b32_dpp v84, v82 row_ror:4 row_mask:0xf bank_mask:0xf bound_ctrl:1
	v_pk_add_f32 v[82:83], v[82:83], v[84:85]
	v_cndmask_b32_e64 v80, v81, v80, s[0:1]
	v_mul_f32_e32 v81, 0x45800000, v86
	v_mov_b32_dpp v85, v83 row_ror:2 row_mask:0xf bank_mask:0xf bound_ctrl:1
	v_mov_b32_dpp v84, v82 row_ror:2 row_mask:0xf bank_mask:0xf bound_ctrl:1
	v_pk_add_f32 v[82:83], v[82:83], v[84:85]
	s_nop 1
	v_mov_b32_dpp v85, v83 row_ror:1 row_mask:0xf bank_mask:0xf bound_ctrl:1
	v_mov_b32_dpp v84, v82 row_ror:1 row_mask:0xf bank_mask:0xf bound_ctrl:1
	v_pk_add_f32 v[82:83], v[82:83], v[84:85]
	s_nop 0
	v_pk_fma_f32 v[82:83], v[82:83], s[24:25], v[132:133] op_sel_hi:[1,0,0]
	s_nop 0
	v_mul_f32_e32 v84, 0x4b800000, v83
	v_cmp_gt_f32_e64 s[0:1], s62, v83
	v_cmp_gt_f32_e64 s[4:5], s62, v82
	s_nop 0
	v_cndmask_b32_e64 v83, v83, v84, s[0:1]
	v_mul_f32_e32 v84, 0x4b800000, v82
	v_rsq_f32_e32 v83, v83
	v_cndmask_b32_e64 v82, v82, v84, s[4:5]
	v_rsq_f32_e32 v85, v82
	v_cndmask_b32_e64 v82, v86, v81, s[2:3]
	v_mul_f32_e32 v81, 0x45800000, v83
	v_cndmask_b32_e64 v84, v83, v81, s[0:1]
	v_mul_f32_e32 v81, 0x45800000, v85
	v_cndmask_b32_e64 v86, v85, v81, s[4:5]
	v_add_u32_e32 v81, 48, v128
	v_pk_mul_f32 v[88:89], v[88:89], v[80:81] op_sel_hi:[1,0]
	v_mad_i64_i32 v[90:91], s[0:1], v81, s63, v[134:135]
	v_mul_f32_e32 v72, 0xbfb8aa3b, v89
	v_exp_f32_e32 v72, v72
	s_nop 0
	v_add_f32_e32 v72, 1.0, v72
	v_rcp_f32_e32 v81, v72
	v_mov_b32_e32 v72, v77
	v_pk_mul_f32 v[72:73], v[72:73], v[82:83] op_sel_hi:[1,0]
; __device__ __forceinline__ float fast_silu(float z) { return z * __builtin_amdgcn_rcpf(1.f + __expf(-z)); }
;   __device__ __forceinline__ void operator()(f32x4 (&acc)[2][2][4][2], int brow, int bcol, int wr, int wc, int fr, int fq) const {
;     ...
; #pragma unroll
;     for (int ai = 0; ai < 2; ++ai)
; #pragma unroll
;       for (int m = 0; m < 4; ++m) {
;         int row0 = brow + ai * 128 + wr * 64 + m * 16 + fq * 4;
;         float rs[4];
; #pragma unroll
;         for (int j = 0; j < 4; ++j) rs[j] = rsqrtf(row16_sum(sv[ai][m][j]) * (1.f / 1024.f) + 1e-6f);
; #pragma unroll
;         for (int n = 0; n < 2; ++n) {
;           float a[4];
; #pragma unroll
;           for (int j = 0; j < 4; ++j) {
;             float g = acc[ai][0][m][n][j] * rs[j], u = acc[ai][1][m][n][j] * rs[j];
;             a[j] = fast_silu(g) * u;
;           }
;           store_rm4(act, 2816, row0, t * 128 + wc * 32 + n * 16 + fr, a[0], a[1], a[2], a[3], fr & 1);
;         }
;         __builtin_amdgcn_sched_barrier(0);
;       }
	v_mul_f32_e32 v81, v89, v81
	v_mul_f32_e32 v81, v88, v81
	v_mov_b32_e32 v88, v78
	v_mov_b32_e32 v89, v74
	v_pk_mul_f32 v[88:89], v[88:89], v[84:85] op_sel_hi:[1,0]
	v_mul_f32_e32 v77, 0xbfb8aa3b, v73
	v_mul_f32_e32 v74, 0xbfb8aa3b, v89
	v_exp_f32_e32 v78, v74
	v_mov_b32_e32 v74, v79
	v_exp_f32_e32 v83, v77
	v_pk_mul_f32 v[74:75], v[74:75], v[86:87] op_sel_hi:[1,0]
	v_add_f32_e32 v78, 1.0, v78
	v_mul_f32_e32 v79, 0xbfb8aa3b, v75
	v_exp_f32_e32 v79, v79
	v_add_f32_e32 v83, 1.0, v83
	v_rcp_f32_e32 v83, v83
	v_rcp_f32_e32 v78, v78
	v_add_f32_e32 v79, 1.0, v79
	v_rcp_f32_e32 v79, v79
	v_mul_f32_e32 v73, v73, v83
	v_mul_f32_e32 v72, v72, v73
	v_mul_f32_e32 v73, v89, v78
	v_mul_f32_e32 v78, v88, v73
	v_mul_f32_e32 v73, v75, v79
	v_mul_f32_e32 v79, v74, v73
	v_cndmask_b32_e32 v73, v81, v72, vcc
	v_mov_b32_e32 v75, v64
	v_mad_i64_i32 v[76:77], s[0:1], v76, s63, v[134:135]
	v_mov_b32_dpp v73, v73 quad_perm:[1,0,3,2] row_mask:0xf bank_mask:0xf bound_ctrl:1
	v_cndmask_b32_e32 v74, v73, v81, vcc
	v_cndmask_b32_e32 v72, v72, v73, vcc
	v_cvt_pk_bf16_f32 v74, v74, v72
	v_lshl_add_u64 v[72:73], v[90:91], 0, v[120:121]
	global_store_dword v[72:73], v74, off
	v_cndmask_b32_e32 v74, v78, v79, vcc
	v_lshl_add_u64 v[76:77], v[76:77], 0, v[120:121]
	s_nop 0
	v_mov_b32_dpp v81, v74 quad_perm:[1,0,3,2] row_mask:0xf bank_mask:0xf bound_ctrl:1
	v_mov_b32_e32 v74, v68
	v_pk_mul_f32 v[74:75], v[74:75], v[80:81] op_sel_hi:[1,0]
	v_cndmask_b32_e32 v78, v81, v78, vcc
	v_mul_f32_e32 v64, 0xbfb8aa3b, v75
	v_exp_f32_e32 v64, v64
	v_cndmask_b32_e32 v68, v79, v81, vcc
	v_cvt_pk_bf16_f32 v68, v78, v68
	global_store_dword v[76:77], v68, off
	v_add_f32_e32 v64, 1.0, v64
	v_rcp_f32_e32 v78, v64
	v_mov_b32_e32 v64, v69
	v_pk_mul_f32 v[64:65], v[64:65], v[82:83] op_sel_hi:[1,0]
	v_mul_f32_e32 v68, v75, v78
	v_mul_f32_e32 v69, 0xbfb8aa3b, v65
	v_exp_f32_e32 v69, v69
	v_mul_f32_e32 v74, v74, v68
	v_add_f32_e32 v68, 1.0, v69
	v_rcp_f32_e32 v75, v68
	v_mov_b32_e32 v68, v70
	v_mov_b32_e32 v69, v66
	v_pk_mul_f32 v[68:69], v[68:69], v[84:85] op_sel_hi:[1,0]
	v_mul_f32_e32 v65, v65, v75
	v_mul_f32_e32 v66, 0xbfb8aa3b, v69
	v_exp_f32_e32 v70, v66
	v_mov_b32_e32 v66, v71
	v_pk_mul_f32 v[66:67], v[66:67], v[86:87] op_sel_hi:[1,0]
	v_mul_f32_e32 v64, v64, v65
	v_mul_f32_e32 v71, 0xbfb8aa3b, v67
	v_exp_f32_e32 v71, v71
	v_add_f32_e32 v70, 1.0, v70
	v_rcp_f32_e32 v70, v70
	v_add_f32_e32 v71, 1.0, v71
	v_rcp_f32_e32 v71, v71
	v_mul_f32_e32 v65, v69, v70
	v_mul_f32_e32 v65, v68, v65
	v_mul_f32_e32 v67, v67, v71
	v_mul_f32_e32 v66, v66, v67
	v_cndmask_b32_e32 v67, v74, v64, vcc
	s_nop 1
	v_mov_b32_dpp v67, v67 quad_perm:[1,0,3,2] row_mask:0xf bank_mask:0xf bound_ctrl:1
	v_cndmask_b32_e32 v68, v67, v74, vcc
	v_cndmask_b32_e32 v64, v64, v67, vcc
	v_cvt_pk_bf16_f32 v64, v68, v64
	global_store_dword v[72:73], v64, off offset:32
	v_cndmask_b32_e32 v64, v65, v66, vcc
	s_nop 1
	v_mov_b32_dpp v64, v64 quad_perm:[1,0,3,2] row_mask:0xf bank_mask:0xf bound_ctrl:1
	v_cndmask_b32_e32 v65, v64, v65, vcc
	v_cndmask_b32_e32 v64, v66, v64, vcc
	v_cvt_pk_bf16_f32 v64, v65, v64
	global_store_dword v[76:77], v64, off offset:32
	v_mov_b32_dpp v65, v149 row_ror:8 row_mask:0xf bank_mask:0xf bound_ctrl:1
	v_mov_b32_dpp v64, v148 row_ror:8 row_mask:0xf bank_mask:0xf bound_ctrl:1
	v_pk_add_f32 v[64:65], v[148:149], v[64:65]
	v_mov_b32_e32 v72, v60
	v_mov_b32_e32 v73, v56
	v_mov_b32_dpp v67, v65 row_ror:4 row_mask:0xf bank_mask:0xf bound_ctrl:1
	v_mov_b32_dpp v66, v64 row_ror:4 row_mask:0xf bank_mask:0xf bound_ctrl:1
	v_pk_add_f32 v[64:65], v[64:65], v[66:67]
	v_add_u32_e32 v71, 0x80, v128
	v_add_u32_e32 v60, 0x82, v128
	v_mov_b32_dpp v67, v65 row_ror:2 row_mask:0xf bank_mask:0xf bound_ctrl:1
	v_mov_b32_dpp v66, v64 row_ror:2 row_mask:0xf bank_mask:0xf bound_ctrl:1
	v_pk_add_f32 v[64:65], v[64:65], v[66:67]
	s_nop 1
	v_mov_b32_dpp v67, v65 row_ror:1 row_mask:0xf bank_mask:0xf bound_ctrl:1
	v_mov_b32_dpp v66, v64 row_ror:1 row_mask:0xf bank_mask:0xf bound_ctrl:1
	v_pk_add_f32 v[64:65], v[64:65], v[66:67]
	v_mov_b32_dpp v67, v147 row_ror:8 row_mask:0xf bank_mask:0xf bound_ctrl:1
	v_pk_fma_f32 v[64:65], v[64:65], s[24:25], v[132:133] op_sel_hi:[1,0,0]
	s_nop 0
	v_mul_f32_e32 v66, 0x4b800000, v65
	v_cmp_gt_f32_e64 s[0:1], s62, v65
	v_cmp_gt_f32_e64 s[2:3], s62, v64
	s_nop 0
	v_cndmask_b32_e64 v65, v65, v66, s[0:1]
	v_mul_f32_e32 v66, 0x4b800000, v64
	v_cndmask_b32_e64 v64, v64, v66, s[2:3]
	v_rsq_f32_e32 v65, v65
	v_mov_b32_dpp v66, v146 row_ror:8 row_mask:0xf bank_mask:0xf bound_ctrl:1
	v_pk_add_f32 v[66:67], v[146:147], v[66:67]
	v_rsq_f32_e32 v70, v64
	v_mul_f32_e32 v64, 0x45800000, v65
	v_mov_b32_dpp v69, v67 row_ror:4 row_mask:0xf bank_mask:0xf bound_ctrl:1
	v_mov_b32_dpp v68, v66 row_ror:4 row_mask:0xf bank_mask:0xf bound_ctrl:1
	v_pk_add_f32 v[66:67], v[66:67], v[68:69]
	v_cndmask_b32_e64 v64, v65, v64, s[0:1]
	v_mul_f32_e32 v65, 0x45800000, v70
	v_mov_b32_dpp v69, v67 row_ror:2 row_mask:0xf bank_mask:0xf bound_ctrl:1
	v_mov_b32_dpp v68, v66 row_ror:2 row_mask:0xf bank_mask:0xf bound_ctrl:1
	v_pk_add_f32 v[66:67], v[66:67], v[68:69]
	s_nop 1
	v_mov_b32_dpp v69, v67 row_ror:1 row_mask:0xf bank_mask:0xf bound_ctrl:1
	v_mov_b32_dpp v68, v66 row_ror:1 row_mask:0xf bank_mask:0xf bound_ctrl:1
	v_pk_add_f32 v[66:67], v[66:67], v[68:69]
	s_nop 0
	v_pk_fma_f32 v[66:67], v[66:67], s[24:25], v[132:133] op_sel_hi:[1,0,0]
	s_nop 0
	v_mul_f32_e32 v68, 0x4b800000, v67
	v_cmp_gt_f32_e64 s[0:1], s62, v67
	v_cmp_gt_f32_e64 s[4:5], s62, v66
	s_nop 0
	v_cndmask_b32_e64 v67, v67, v68, s[0:1]
	v_mul_f32_e32 v68, 0x4b800000, v66
	v_rsq_f32_e32 v67, v67
	v_cndmask_b32_e64 v66, v66, v68, s[4:5]
	v_rsq_f32_e32 v69, v66
	v_cndmask_b32_e64 v66, v70, v65, s[2:3]
; __device__ __forceinline__ float fast_silu(float z) { return z * __builtin_amdgcn_rcpf(1.f + __expf(-z)); }
;   __device__ __forceinline__ void operator()(f32x4 (&acc)[2][2][4][2], int brow, int bcol, int wr, int wc, int fr, int fq) const {
;     ...
; #pragma unroll
;     for (int ai = 0; ai < 2; ++ai)
; #pragma unroll
;       for (int m = 0; m < 4; ++m) {
;         int row0 = brow + ai * 128 + wr * 64 + m * 16 + fq * 4;
;         float rs[4];
; #pragma unroll
;         for (int j = 0; j < 4; ++j) rs[j] = rsqrtf(row16_sum(sv[ai][m][j]) * (1.f / 1024.f) + 1e-6f);
; #pragma unroll
;         for (int n = 0; n < 2; ++n) {
;           float a[4];
; #pragma unroll
;           for (int j = 0; j < 4; ++j) {
;             float g = acc[ai][0][m][n][j] * rs[j], u = acc[ai][1][m][n][j] * rs[j];
;             a[j] = fast_silu(g) * u;
;           }
;           store_rm4(act, 2816, row0, t * 128 + wc * 32 + n * 16 + fr, a[0], a[1], a[2], a[3], fr & 1);
;         }
;         __builtin_amdgcn_sched_barrier(0);
;       }
	v_mul_f32_e32 v65, 0x45800000, v67
	v_cndmask_b32_e64 v68, v67, v65, s[0:1]
	v_mul_f32_e32 v65, 0x45800000, v69
	v_pk_mul_f32 v[72:73], v[72:73], v[64:65] op_sel_hi:[1,0]
	v_cndmask_b32_e64 v70, v69, v65, s[4:5]
	v_mul_f32_e32 v56, 0xbfb8aa3b, v73
	v_exp_f32_e32 v56, v56
	v_mad_i64_i32 v[74:75], s[0:1], v71, s63, v[134:135]
	v_add_f32_e32 v56, 1.0, v56
	v_rcp_f32_e32 v65, v56
	v_mov_b32_e32 v56, v61
	v_pk_mul_f32 v[56:57], v[56:57], v[66:67] op_sel_hi:[1,0]
	v_mul_f32_e32 v65, v73, v65
	v_mul_f32_e32 v65, v72, v65
	v_mov_b32_e32 v72, v62
	v_mov_b32_e32 v73, v58
	v_pk_mul_f32 v[72:73], v[72:73], v[68:69] op_sel_hi:[1,0]
	v_mul_f32_e32 v61, 0xbfb8aa3b, v57
	v_mul_f32_e32 v58, 0xbfb8aa3b, v73
	v_exp_f32_e32 v62, v58
	v_mov_b32_e32 v58, v63
	v_exp_f32_e32 v67, v61
	v_pk_mul_f32 v[58:59], v[58:59], v[70:71] op_sel_hi:[1,0]
	v_add_f32_e32 v62, 1.0, v62
	v_mul_f32_e32 v63, 0xbfb8aa3b, v59
	v_exp_f32_e32 v63, v63
	v_add_f32_e32 v67, 1.0, v67
	v_rcp_f32_e32 v67, v67
	v_rcp_f32_e32 v62, v62
	v_add_f32_e32 v63, 1.0, v63
	v_rcp_f32_e32 v63, v63
	v_mul_f32_e32 v57, v57, v67
	v_mul_f32_e32 v56, v56, v57
	v_mul_f32_e32 v57, v73, v62
	v_mul_f32_e32 v62, v72, v57
	v_mul_f32_e32 v57, v59, v63
	v_mul_f32_e32 v63, v58, v57
	v_cndmask_b32_e32 v57, v65, v56, vcc
	v_mov_b32_e32 v59, v48
	v_mad_i64_i32 v[60:61], s[0:1], v60, s63, v[134:135]
	v_mov_b32_dpp v57, v57 quad_perm:[1,0,3,2] row_mask:0xf bank_mask:0xf bound_ctrl:1
	v_cndmask_b32_e32 v58, v57, v65, vcc
	v_cndmask_b32_e32 v56, v56, v57, vcc
	v_cvt_pk_bf16_f32 v58, v58, v56
	v_lshl_add_u64 v[56:57], v[74:75], 0, v[120:121]
	global_store_dword v[56:57], v58, off
	v_cndmask_b32_e32 v58, v62, v63, vcc
	v_lshl_add_u64 v[60:61], v[60:61], 0, v[120:121]
	s_nop 0
	v_mov_b32_dpp v65, v58 quad_perm:[1,0,3,2] row_mask:0xf bank_mask:0xf bound_ctrl:1
	v_mov_b32_e32 v58, v52
	v_pk_mul_f32 v[58:59], v[58:59], v[64:65] op_sel_hi:[1,0]
	v_cndmask_b32_e32 v62, v65, v62, vcc
	v_mul_f32_e32 v48, 0xbfb8aa3b, v59
	v_exp_f32_e32 v48, v48
	v_cndmask_b32_e32 v52, v63, v65, vcc
	v_cvt_pk_bf16_f32 v52, v62, v52
	global_store_dword v[60:61], v52, off
	v_add_f32_e32 v48, 1.0, v48
	v_rcp_f32_e32 v62, v48
	v_mov_b32_e32 v48, v53
	v_pk_mul_f32 v[48:49], v[48:49], v[66:67] op_sel_hi:[1,0]
	v_mul_f32_e32 v52, v59, v62
	v_mul_f32_e32 v53, 0xbfb8aa3b, v49
	v_exp_f32_e32 v53, v53
	v_mul_f32_e32 v58, v58, v52
	v_add_f32_e32 v52, 1.0, v53
	v_rcp_f32_e32 v59, v52
	v_mov_b32_e32 v52, v54
	v_mov_b32_e32 v53, v50
	v_pk_mul_f32 v[52:53], v[52:53], v[68:69] op_sel_hi:[1,0]
	v_mul_f32_e32 v49, v49, v59
	v_mul_f32_e32 v50, 0xbfb8aa3b, v53
	v_exp_f32_e32 v54, v50
	v_mov_b32_e32 v50, v55
	v_pk_mul_f32 v[50:51], v[50:51], v[70:71] op_sel_hi:[1,0]
	v_mul_f32_e32 v48, v48, v49
	v_mul_f32_e32 v55, 0xbfb8aa3b, v51
	v_exp_f32_e32 v55, v55
	v_add_f32_e32 v54, 1.0, v54
	v_rcp_f32_e32 v54, v54
	v_add_f32_e32 v55, 1.0, v55
	v_rcp_f32_e32 v55, v55
	v_mul_f32_e32 v49, v53, v54
	v_mul_f32_e32 v49, v52, v49
	v_mul_f32_e32 v51, v51, v55
	v_mul_f32_e32 v50, v50, v51
	v_cndmask_b32_e32 v51, v58, v48, vcc
	s_nop 1
	v_mov_b32_dpp v51, v51 quad_perm:[1,0,3,2] row_mask:0xf bank_mask:0xf bound_ctrl:1
	v_cndmask_b32_e32 v52, v51, v58, vcc
	v_cndmask_b32_e32 v48, v48, v51, vcc
	v_cvt_pk_bf16_f32 v48, v52, v48
	global_store_dword v[56:57], v48, off offset:32
	v_cndmask_b32_e32 v48, v49, v50, vcc
	s_nop 1
	v_mov_b32_dpp v48, v48 quad_perm:[1,0,3,2] row_mask:0xf bank_mask:0xf bound_ctrl:1
	v_cndmask_b32_e32 v49, v48, v49, vcc
	v_cndmask_b32_e32 v48, v50, v48, vcc
	v_cvt_pk_bf16_f32 v48, v49, v48
	global_store_dword v[60:61], v48, off offset:32
	v_mov_b32_dpp v49, v145 row_ror:8 row_mask:0xf bank_mask:0xf bound_ctrl:1
	v_mov_b32_dpp v48, v144 row_ror:8 row_mask:0xf bank_mask:0xf bound_ctrl:1
	v_pk_add_f32 v[48:49], v[144:145], v[48:49]
	v_mov_b32_e32 v56, v44
	v_mov_b32_e32 v57, v40
	v_mov_b32_dpp v51, v49 row_ror:4 row_mask:0xf bank_mask:0xf bound_ctrl:1
	v_mov_b32_dpp v50, v48 row_ror:4 row_mask:0xf bank_mask:0xf bound_ctrl:1
	v_pk_add_f32 v[48:49], v[48:49], v[50:51]
	v_add_u32_e32 v44, 0x92, v128
	s_nop 0
	v_mov_b32_dpp v51, v49 row_ror:2 row_mask:0xf bank_mask:0xf bound_ctrl:1
	v_mov_b32_dpp v50, v48 row_ror:2 row_mask:0xf bank_mask:0xf bound_ctrl:1
	v_pk_add_f32 v[48:49], v[48:49], v[50:51]
	s_nop 1
	v_mov_b32_dpp v51, v49 row_ror:1 row_mask:0xf bank_mask:0xf bound_ctrl:1
	v_mov_b32_dpp v50, v48 row_ror:1 row_mask:0xf bank_mask:0xf bound_ctrl:1
	v_pk_add_f32 v[48:49], v[48:49], v[50:51]
	v_mov_b32_dpp v51, v143 row_ror:8 row_mask:0xf bank_mask:0xf bound_ctrl:1
	v_pk_fma_f32 v[48:49], v[48:49], s[24:25], v[132:133] op_sel_hi:[1,0,0]
	s_nop 0
	v_mul_f32_e32 v50, 0x4b800000, v49
	v_cmp_gt_f32_e64 s[0:1], s62, v49
	v_cmp_gt_f32_e64 s[2:3], s62, v48
	s_nop 0
	v_cndmask_b32_e64 v49, v49, v50, s[0:1]
	v_mul_f32_e32 v50, 0x4b800000, v48
	v_cndmask_b32_e64 v48, v48, v50, s[2:3]
	v_rsq_f32_e32 v49, v49
	v_mov_b32_dpp v50, v142 row_ror:8 row_mask:0xf bank_mask:0xf bound_ctrl:1
	v_pk_add_f32 v[50:51], v[142:143], v[50:51]
	v_rsq_f32_e32 v54, v48
	v_mul_f32_e32 v48, 0x45800000, v49
	v_mov_b32_dpp v53, v51 row_ror:4 row_mask:0xf bank_mask:0xf bound_ctrl:1
	v_mov_b32_dpp v52, v50 row_ror:4 row_mask:0xf bank_mask:0xf bound_ctrl:1
	v_pk_add_f32 v[50:51], v[50:51], v[52:53]
	v_cndmask_b32_e64 v48, v49, v48, s[0:1]
	v_mul_f32_e32 v49, 0x45800000, v54
	v_mov_b32_dpp v53, v51 row_ror:2 row_mask:0xf bank_mask:0xf bound_ctrl:1
	v_mov_b32_dpp v52, v50 row_ror:2 row_mask:0xf bank_mask:0xf bound_ctrl:1
	v_pk_add_f32 v[50:51], v[50:51], v[52:53]
	s_nop 1
	v_mov_b32_dpp v53, v51 row_ror:1 row_mask:0xf bank_mask:0xf bound_ctrl:1
	v_mov_b32_dpp v52, v50 row_ror:1 row_mask:0xf bank_mask:0xf bound_ctrl:1
; __device__ __forceinline__ float fast_silu(float z) { return z * __builtin_amdgcn_rcpf(1.f + __expf(-z)); }
;   __device__ __forceinline__ void operator()(f32x4 (&acc)[2][2][4][2], int brow, int bcol, int wr, int wc, int fr, int fq) const {
;     ...
; #pragma unroll
;     for (int ai = 0; ai < 2; ++ai)
; #pragma unroll
;       for (int m = 0; m < 4; ++m) {
;         int row0 = brow + ai * 128 + wr * 64 + m * 16 + fq * 4;
;         float rs[4];
; #pragma unroll
;         for (int j = 0; j < 4; ++j) rs[j] = rsqrtf(row16_sum(sv[ai][m][j]) * (1.f / 1024.f) + 1e-6f);
; #pragma unroll
;         for (int n = 0; n < 2; ++n) {
;           float a[4];
; #pragma unroll
;           for (int j = 0; j < 4; ++j) {
;             float g = acc[ai][0][m][n][j] * rs[j], u = acc[ai][1][m][n][j] * rs[j];
;             a[j] = fast_silu(g) * u;
;           }
;           store_rm4(act, 2816, row0, t * 128 + wc * 32 + n * 16 + fr, a[0], a[1], a[2], a[3], fr & 1);
;         }
;         __builtin_amdgcn_sched_barrier(0);
;       }
	v_pk_add_f32 v[50:51], v[50:51], v[52:53]
	s_nop 0
	v_pk_fma_f32 v[50:51], v[50:51], s[24:25], v[132:133] op_sel_hi:[1,0,0]
	s_nop 0
	v_mul_f32_e32 v52, 0x4b800000, v51
	v_cmp_gt_f32_e64 s[0:1], s62, v51
	v_cmp_gt_f32_e64 s[4:5], s62, v50
	s_nop 0
	v_cndmask_b32_e64 v51, v51, v52, s[0:1]
	v_mul_f32_e32 v52, 0x4b800000, v50
	v_rsq_f32_e32 v51, v51
	v_cndmask_b32_e64 v50, v50, v52, s[4:5]
	v_rsq_f32_e32 v53, v50
	v_cndmask_b32_e64 v50, v54, v49, s[2:3]
	v_mul_f32_e32 v49, 0x45800000, v51
	v_cndmask_b32_e64 v52, v51, v49, s[0:1]
	v_mul_f32_e32 v49, 0x45800000, v53
	v_cndmask_b32_e64 v54, v53, v49, s[4:5]
	v_add_u32_e32 v49, 0x90, v128
	v_pk_mul_f32 v[56:57], v[56:57], v[48:49] op_sel_hi:[1,0]
	v_mad_i64_i32 v[58:59], s[0:1], v49, s63, v[134:135]
	v_mul_f32_e32 v40, 0xbfb8aa3b, v57
	v_exp_f32_e32 v40, v40
	s_nop 0
	v_add_f32_e32 v40, 1.0, v40
	v_rcp_f32_e32 v49, v40
	v_mov_b32_e32 v40, v45
	v_pk_mul_f32 v[40:41], v[40:41], v[50:51] op_sel_hi:[1,0]
	v_mul_f32_e32 v49, v57, v49
	v_mul_f32_e32 v49, v56, v49
	v_mov_b32_e32 v56, v46
	v_mov_b32_e32 v57, v42
	v_pk_mul_f32 v[56:57], v[56:57], v[52:53] op_sel_hi:[1,0]
	v_mul_f32_e32 v45, 0xbfb8aa3b, v41
	v_mul_f32_e32 v42, 0xbfb8aa3b, v57
	v_exp_f32_e32 v46, v42
	v_mov_b32_e32 v42, v47
	v_exp_f32_e32 v51, v45
	v_pk_mul_f32 v[42:43], v[42:43], v[54:55] op_sel_hi:[1,0]
	v_add_f32_e32 v46, 1.0, v46
	v_mul_f32_e32 v47, 0xbfb8aa3b, v43
	v_exp_f32_e32 v47, v47
	v_add_f32_e32 v51, 1.0, v51
	v_rcp_f32_e32 v51, v51
	v_rcp_f32_e32 v46, v46
	v_add_f32_e32 v47, 1.0, v47
	v_rcp_f32_e32 v47, v47
	v_mul_f32_e32 v41, v41, v51
	v_mul_f32_e32 v40, v40, v41
	v_mul_f32_e32 v41, v57, v46
	v_mul_f32_e32 v46, v56, v41
	v_mul_f32_e32 v41, v43, v47
	v_mul_f32_e32 v47, v42, v41
	v_cndmask_b32_e32 v41, v49, v40, vcc
	v_mov_b32_e32 v43, v32
	v_mad_i64_i32 v[44:45], s[0:1], v44, s63, v[134:135]
	v_mov_b32_dpp v41, v41 quad_perm:[1,0,3,2] row_mask:0xf bank_mask:0xf bound_ctrl:1
	v_cndmask_b32_e32 v42, v41, v49, vcc
	v_cndmask_b32_e32 v40, v40, v41, vcc
	v_cvt_pk_bf16_f32 v42, v42, v40
	v_lshl_add_u64 v[40:41], v[58:59], 0, v[120:121]
	global_store_dword v[40:41], v42, off
	v_cndmask_b32_e32 v42, v46, v47, vcc
	v_lshl_add_u64 v[44:45], v[44:45], 0, v[120:121]
	s_nop 0
	v_mov_b32_dpp v49, v42 quad_perm:[1,0,3,2] row_mask:0xf bank_mask:0xf bound_ctrl:1
	v_mov_b32_e32 v42, v36
	v_pk_mul_f32 v[42:43], v[42:43], v[48:49] op_sel_hi:[1,0]
	v_cndmask_b32_e32 v46, v49, v46, vcc
	v_mul_f32_e32 v32, 0xbfb8aa3b, v43
	v_exp_f32_e32 v32, v32
	v_cndmask_b32_e32 v36, v47, v49, vcc
	v_cvt_pk_bf16_f32 v36, v46, v36
	global_store_dword v[44:45], v36, off
	v_add_f32_e32 v32, 1.0, v32
	v_rcp_f32_e32 v46, v32
	v_mov_b32_e32 v32, v37
	v_pk_mul_f32 v[32:33], v[32:33], v[50:51] op_sel_hi:[1,0]
	v_mul_f32_e32 v36, v43, v46
	v_mul_f32_e32 v37, 0xbfb8aa3b, v33
	v_exp_f32_e32 v37, v37
	v_mul_f32_e32 v42, v42, v36
	v_add_f32_e32 v36, 1.0, v37
	v_rcp_f32_e32 v43, v36
	v_mov_b32_e32 v36, v38
	v_mov_b32_e32 v37, v34
	v_pk_mul_f32 v[36:37], v[36:37], v[52:53] op_sel_hi:[1,0]
	v_mul_f32_e32 v33, v33, v43
	v_mul_f32_e32 v34, 0xbfb8aa3b, v37
	v_exp_f32_e32 v38, v34
	v_mov_b32_e32 v34, v39
	v_pk_mul_f32 v[34:35], v[34:35], v[54:55] op_sel_hi:[1,0]
	v_mul_f32_e32 v32, v32, v33
	v_mul_f32_e32 v39, 0xbfb8aa3b, v35
	v_exp_f32_e32 v39, v39
	v_add_f32_e32 v38, 1.0, v38
	v_rcp_f32_e32 v38, v38
	v_add_f32_e32 v39, 1.0, v39
	v_rcp_f32_e32 v39, v39
	v_mul_f32_e32 v33, v37, v38
	v_mul_f32_e32 v33, v36, v33
	v_mul_f32_e32 v35, v35, v39
	v_mul_f32_e32 v34, v34, v35
	v_cndmask_b32_e32 v35, v42, v32, vcc
	s_nop 1
	v_mov_b32_dpp v35, v35 quad_perm:[1,0,3,2] row_mask:0xf bank_mask:0xf bound_ctrl:1
	v_cndmask_b32_e32 v36, v35, v42, vcc
	v_cndmask_b32_e32 v32, v32, v35, vcc
	v_cvt_pk_bf16_f32 v32, v36, v32
	global_store_dword v[40:41], v32, off offset:32
	v_cndmask_b32_e32 v32, v33, v34, vcc
	s_nop 1
	v_mov_b32_dpp v32, v32 quad_perm:[1,0,3,2] row_mask:0xf bank_mask:0xf bound_ctrl:1
	v_cndmask_b32_e32 v33, v32, v33, vcc
	v_cndmask_b32_e32 v32, v34, v32, vcc
	v_cvt_pk_bf16_f32 v32, v33, v32
	global_store_dword v[44:45], v32, off offset:32
	v_mov_b32_dpp v33, v141 row_ror:8 row_mask:0xf bank_mask:0xf bound_ctrl:1
	v_mov_b32_dpp v32, v140 row_ror:8 row_mask:0xf bank_mask:0xf bound_ctrl:1
	v_pk_add_f32 v[32:33], v[140:141], v[32:33]
	v_mov_b32_e32 v40, v28
	v_mov_b32_e32 v41, v24
	v_mov_b32_dpp v35, v33 row_ror:4 row_mask:0xf bank_mask:0xf bound_ctrl:1
	v_mov_b32_dpp v34, v32 row_ror:4 row_mask:0xf bank_mask:0xf bound_ctrl:1
	v_pk_add_f32 v[32:33], v[32:33], v[34:35]
	v_add_u32_e32 v28, 0xa2, v128
	s_nop 0
	v_mov_b32_dpp v35, v33 row_ror:2 row_mask:0xf bank_mask:0xf bound_ctrl:1
	v_mov_b32_dpp v34, v32 row_ror:2 row_mask:0xf bank_mask:0xf bound_ctrl:1
	v_pk_add_f32 v[32:33], v[32:33], v[34:35]
	s_nop 1
	v_mov_b32_dpp v35, v33 row_ror:1 row_mask:0xf bank_mask:0xf bound_ctrl:1
	v_mov_b32_dpp v34, v32 row_ror:1 row_mask:0xf bank_mask:0xf bound_ctrl:1
	v_pk_add_f32 v[32:33], v[32:33], v[34:35]
	v_mov_b32_dpp v35, v139 row_ror:8 row_mask:0xf bank_mask:0xf bound_ctrl:1
	v_pk_fma_f32 v[32:33], v[32:33], s[24:25], v[132:133] op_sel_hi:[1,0,0]
	s_nop 0
	v_mul_f32_e32 v34, 0x4b800000, v33
	v_cmp_gt_f32_e64 s[0:1], s62, v33
	v_cmp_gt_f32_e64 s[2:3], s62, v32
	s_nop 0
	v_cndmask_b32_e64 v33, v33, v34, s[0:1]
	v_mul_f32_e32 v34, 0x4b800000, v32
	v_cndmask_b32_e64 v32, v32, v34, s[2:3]
	v_rsq_f32_e32 v33, v33
	v_mov_b32_dpp v34, v138 row_ror:8 row_mask:0xf bank_mask:0xf bound_ctrl:1
	v_pk_add_f32 v[34:35], v[138:139], v[34:35]
	v_rsq_f32_e32 v38, v32
	v_mul_f32_e32 v32, 0x45800000, v33
	v_mov_b32_dpp v37, v35 row_ror:4 row_mask:0xf bank_mask:0xf bound_ctrl:1
	v_mov_b32_dpp v36, v34 row_ror:4 row_mask:0xf bank_mask:0xf bound_ctrl:1
; __device__ __forceinline__ float fast_silu(float z) { return z * __builtin_amdgcn_rcpf(1.f + __expf(-z)); }
;   __device__ __forceinline__ void operator()(f32x4 (&acc)[2][2][4][2], int brow, int bcol, int wr, int wc, int fr, int fq) const {
;     ...
; #pragma unroll
;     for (int ai = 0; ai < 2; ++ai)
; #pragma unroll
;       for (int m = 0; m < 4; ++m) {
;         int row0 = brow + ai * 128 + wr * 64 + m * 16 + fq * 4;
;         float rs[4];
; #pragma unroll
;         for (int j = 0; j < 4; ++j) rs[j] = rsqrtf(row16_sum(sv[ai][m][j]) * (1.f / 1024.f) + 1e-6f);
; #pragma unroll
;         for (int n = 0; n < 2; ++n) {
;           float a[4];
; #pragma unroll
;           for (int j = 0; j < 4; ++j) {
;             float g = acc[ai][0][m][n][j] * rs[j], u = acc[ai][1][m][n][j] * rs[j];
;             a[j] = fast_silu(g) * u;
;           }
;           store_rm4(act, 2816, row0, t * 128 + wc * 32 + n * 16 + fr, a[0], a[1], a[2], a[3], fr & 1);
;         }
;         __builtin_amdgcn_sched_barrier(0);
;       }
	v_pk_add_f32 v[34:35], v[34:35], v[36:37]
	v_cndmask_b32_e64 v32, v33, v32, s[0:1]
	v_mul_f32_e32 v33, 0x45800000, v38
	v_mov_b32_dpp v37, v35 row_ror:2 row_mask:0xf bank_mask:0xf bound_ctrl:1
	v_mov_b32_dpp v36, v34 row_ror:2 row_mask:0xf bank_mask:0xf bound_ctrl:1
	v_pk_add_f32 v[34:35], v[34:35], v[36:37]
	s_nop 1
	v_mov_b32_dpp v37, v35 row_ror:1 row_mask:0xf bank_mask:0xf bound_ctrl:1
	v_mov_b32_dpp v36, v34 row_ror:1 row_mask:0xf bank_mask:0xf bound_ctrl:1
	v_pk_add_f32 v[34:35], v[34:35], v[36:37]
	s_nop 0
	v_pk_fma_f32 v[34:35], v[34:35], s[24:25], v[132:133] op_sel_hi:[1,0,0]
	s_nop 0
	v_mul_f32_e32 v36, 0x4b800000, v35
	v_cmp_gt_f32_e64 s[0:1], s62, v35
	v_cmp_gt_f32_e64 s[4:5], s62, v34
	s_nop 0
	v_cndmask_b32_e64 v35, v35, v36, s[0:1]
	v_mul_f32_e32 v36, 0x4b800000, v34
	v_rsq_f32_e32 v35, v35
	v_cndmask_b32_e64 v34, v34, v36, s[4:5]
	v_rsq_f32_e32 v37, v34
	v_cndmask_b32_e64 v34, v38, v33, s[2:3]
	v_mul_f32_e32 v33, 0x45800000, v35
	v_cndmask_b32_e64 v36, v35, v33, s[0:1]
	v_mul_f32_e32 v33, 0x45800000, v37
	v_cndmask_b32_e64 v38, v37, v33, s[4:5]
	v_add_u32_e32 v33, 0xa0, v128
	v_pk_mul_f32 v[40:41], v[40:41], v[32:33] op_sel_hi:[1,0]
	v_mad_i64_i32 v[42:43], s[0:1], v33, s63, v[134:135]
	v_mul_f32_e32 v24, 0xbfb8aa3b, v41
	v_exp_f32_e32 v24, v24
	s_nop 0
	v_add_f32_e32 v24, 1.0, v24
	v_rcp_f32_e32 v33, v24
	v_mov_b32_e32 v24, v29
	v_pk_mul_f32 v[24:25], v[24:25], v[34:35] op_sel_hi:[1,0]
	v_mul_f32_e32 v33, v41, v33
	v_mul_f32_e32 v33, v40, v33
	v_mov_b32_e32 v40, v30
	v_mov_b32_e32 v41, v26
	v_pk_mul_f32 v[40:41], v[40:41], v[36:37] op_sel_hi:[1,0]
	v_mul_f32_e32 v29, 0xbfb8aa3b, v25
	v_mul_f32_e32 v26, 0xbfb8aa3b, v41
	v_exp_f32_e32 v30, v26
	v_mov_b32_e32 v26, v31
	v_exp_f32_e32 v35, v29
	v_pk_mul_f32 v[26:27], v[26:27], v[38:39] op_sel_hi:[1,0]
	v_add_f32_e32 v30, 1.0, v30
	v_mul_f32_e32 v31, 0xbfb8aa3b, v27
	v_exp_f32_e32 v31, v31
	v_add_f32_e32 v35, 1.0, v35
	v_rcp_f32_e32 v35, v35
	v_rcp_f32_e32 v30, v30
	v_add_f32_e32 v31, 1.0, v31
	v_rcp_f32_e32 v31, v31
	v_mul_f32_e32 v25, v25, v35
	v_mul_f32_e32 v24, v24, v25
	v_mul_f32_e32 v25, v41, v30
	v_mul_f32_e32 v30, v40, v25
	v_mul_f32_e32 v25, v27, v31
	v_mul_f32_e32 v31, v26, v25
	v_cndmask_b32_e32 v25, v33, v24, vcc
	v_mov_b32_e32 v27, v16
	v_mad_i64_i32 v[28:29], s[0:1], v28, s63, v[134:135]
	v_mov_b32_dpp v25, v25 quad_perm:[1,0,3,2] row_mask:0xf bank_mask:0xf bound_ctrl:1
	v_cndmask_b32_e32 v26, v25, v33, vcc
	v_cndmask_b32_e32 v24, v24, v25, vcc
	v_cvt_pk_bf16_f32 v26, v26, v24
	v_lshl_add_u64 v[24:25], v[42:43], 0, v[120:121]
	global_store_dword v[24:25], v26, off
	v_cndmask_b32_e32 v26, v30, v31, vcc
	v_lshl_add_u64 v[28:29], v[28:29], 0, v[120:121]
	s_nop 0
	v_mov_b32_dpp v33, v26 quad_perm:[1,0,3,2] row_mask:0xf bank_mask:0xf bound_ctrl:1
	v_mov_b32_e32 v26, v20
	v_pk_mul_f32 v[26:27], v[26:27], v[32:33] op_sel_hi:[1,0]
	v_cndmask_b32_e32 v30, v33, v30, vcc
	v_mul_f32_e32 v16, 0xbfb8aa3b, v27
	v_exp_f32_e32 v16, v16
	v_cndmask_b32_e32 v20, v31, v33, vcc
	v_cvt_pk_bf16_f32 v20, v30, v20
	global_store_dword v[28:29], v20, off
	v_add_f32_e32 v16, 1.0, v16
	v_rcp_f32_e32 v30, v16
	v_mov_b32_e32 v16, v21
	v_pk_mul_f32 v[16:17], v[16:17], v[34:35] op_sel_hi:[1,0]
	v_mul_f32_e32 v20, v27, v30
	v_mul_f32_e32 v21, 0xbfb8aa3b, v17
	v_exp_f32_e32 v21, v21
	v_mul_f32_e32 v26, v26, v20
	v_add_f32_e32 v20, 1.0, v21
	v_rcp_f32_e32 v27, v20
	v_mov_b32_e32 v20, v22
	v_mov_b32_e32 v21, v18
	v_pk_mul_f32 v[20:21], v[20:21], v[36:37] op_sel_hi:[1,0]
	v_mul_f32_e32 v17, v17, v27
	v_mul_f32_e32 v18, 0xbfb8aa3b, v21
	v_exp_f32_e32 v22, v18
	v_mov_b32_e32 v18, v23
	v_pk_mul_f32 v[18:19], v[18:19], v[38:39] op_sel_hi:[1,0]
	v_mul_f32_e32 v16, v16, v17
	v_mul_f32_e32 v23, 0xbfb8aa3b, v19
	v_exp_f32_e32 v23, v23
	v_add_f32_e32 v22, 1.0, v22
	v_rcp_f32_e32 v22, v22
	v_add_f32_e32 v23, 1.0, v23
	v_rcp_f32_e32 v23, v23
	v_mul_f32_e32 v17, v21, v22
	v_mul_f32_e32 v17, v20, v17
	v_mul_f32_e32 v19, v19, v23
	v_mul_f32_e32 v18, v18, v19
	v_cndmask_b32_e32 v19, v26, v16, vcc
	s_nop 1
	v_mov_b32_dpp v19, v19 quad_perm:[1,0,3,2] row_mask:0xf bank_mask:0xf bound_ctrl:1
	v_cndmask_b32_e32 v20, v19, v26, vcc
	v_cndmask_b32_e32 v16, v16, v19, vcc
	v_cvt_pk_bf16_f32 v16, v20, v16
	global_store_dword v[24:25], v16, off offset:32
	v_cndmask_b32_e32 v16, v17, v18, vcc
	s_nop 1
	v_mov_b32_dpp v16, v16 quad_perm:[1,0,3,2] row_mask:0xf bank_mask:0xf bound_ctrl:1
	v_cndmask_b32_e32 v17, v16, v17, vcc
	v_cndmask_b32_e32 v16, v18, v16, vcc
	v_cvt_pk_bf16_f32 v16, v17, v16
	global_store_dword v[28:29], v16, off offset:32
	v_mov_b32_dpp v17, v137 row_ror:8 row_mask:0xf bank_mask:0xf bound_ctrl:1
	v_mov_b32_dpp v16, v136 row_ror:8 row_mask:0xf bank_mask:0xf bound_ctrl:1
	v_pk_add_f32 v[16:17], v[136:137], v[16:17]
	v_mov_b32_e32 v24, v12
	v_mov_b32_e32 v25, v8
	v_mov_b32_dpp v19, v17 row_ror:4 row_mask:0xf bank_mask:0xf bound_ctrl:1
	v_mov_b32_dpp v18, v16 row_ror:4 row_mask:0xf bank_mask:0xf bound_ctrl:1
	v_pk_add_f32 v[16:17], v[16:17], v[18:19]
	v_add_u32_e32 v12, 0xb2, v128
	s_nop 0
	v_mov_b32_dpp v19, v17 row_ror:2 row_mask:0xf bank_mask:0xf bound_ctrl:1
	v_mov_b32_dpp v18, v16 row_ror:2 row_mask:0xf bank_mask:0xf bound_ctrl:1
	v_pk_add_f32 v[16:17], v[16:17], v[18:19]
	s_nop 1
	v_mov_b32_dpp v19, v17 row_ror:1 row_mask:0xf bank_mask:0xf bound_ctrl:1
	v_mov_b32_dpp v18, v16 row_ror:1 row_mask:0xf bank_mask:0xf bound_ctrl:1
; __device__ __forceinline__ float fast_silu(float z) { return z * __builtin_amdgcn_rcpf(1.f + __expf(-z)); }
; #define WAIT_L(n) asm volatile("s_waitcnt lgkmcnt(" #n ")" ::: "memory")
; #define BAR __builtin_amdgcn_s_barrier()
; template <class Epi>
; __device__ __forceinline__ void gemm_tile(const u16* __restrict__ A, const u16* __restrict__ Bt, int K,
;                                           int brow, int bcol, bool first, bool has_next, int nbrow, int nbcol, Epi epi) {
;     ...
;   WAIT_L(0); BAR;
;     ...
; }
; template <class Epi>
; __device__ __forceinline__ void gemm_phase(const u16* A, const u16* Bt, int K, int nN, Epi epi) {
;   {
;     int x = epi.p.vx, j = epi.p.vj;
;     int li = j;
;     int mg = li / (nN * 8), rem = li % (nN * 8);
;     int brow = (x * 32 + mg * 8 + (rem & 7)) * 256, bcol = (rem >> 3) * 256;
;     for (int rd = 0; rd < nN; ++rd) {
;       int nbrow = 0, nbcol = 0;
;       bool has_next = rd + 1 < nN;
;       if (has_next) {
;         int l2 = (rd + 1) * 32 + j;
;         int mg2 = l2 / (nN * 8), rem2 = l2 % (nN * 8);
;         nbrow = (x * 32 + mg2 * 8 + (rem2 & 7)) * 256; nbcol = (rem2 >> 3) * 256;
;       }
;       gemm_tile(A, Bt, K, brow, bcol, rd == 0, has_next, nbrow, nbcol, epi);
;       brow = nbrow; bcol = nbcol;
;   __device__ __forceinline__ void operator()(f32x4 (&acc)[2][2][4][2], int brow, int bcol, int wr, int wc, int fr, int fq) const {
;     ...
; #pragma unroll
;     for (int ai = 0; ai < 2; ++ai)
; #pragma unroll
;       for (int m = 0; m < 4; ++m) {
;         int row0 = brow + ai * 128 + wr * 64 + m * 16 + fq * 4;
;         float rs[4];
; #pragma unroll
;         for (int j = 0; j < 4; ++j) rs[j] = rsqrtf(row16_sum(sv[ai][m][j]) * (1.f / 1024.f) + 1e-6f);
; #pragma unroll
;         for (int n = 0; n < 2; ++n) {
;           float a[4];
; #pragma unroll
;           for (int j = 0; j < 4; ++j) {
;             float g = acc[ai][0][m][n][j] * rs[j], u = acc[ai][1][m][n][j] * rs[j];
;             a[j] = fast_silu(g) * u;
;           }
;           store_rm4(act, 2816, row0, t * 128 + wc * 32 + n * 16 + fr, a[0], a[1], a[2], a[3], fr & 1);
;         }
;         __builtin_amdgcn_sched_barrier(0);
;       }
	v_pk_add_f32 v[16:17], v[16:17], v[18:19]
	v_mov_b32_dpp v19, v131 row_ror:8 row_mask:0xf bank_mask:0xf bound_ctrl:1
	v_pk_fma_f32 v[16:17], v[16:17], s[24:25], v[132:133] op_sel_hi:[1,0,0]
	s_nop 0
	v_mul_f32_e32 v18, 0x4b800000, v17
	v_cmp_gt_f32_e64 s[0:1], s62, v17
	v_cmp_gt_f32_e64 s[2:3], s62, v16
	s_nop 0
	v_cndmask_b32_e64 v17, v17, v18, s[0:1]
	v_mul_f32_e32 v18, 0x4b800000, v16
	v_cndmask_b32_e64 v16, v16, v18, s[2:3]
	v_rsq_f32_e32 v17, v17
	v_mov_b32_dpp v18, v130 row_ror:8 row_mask:0xf bank_mask:0xf bound_ctrl:1
	v_pk_add_f32 v[18:19], v[130:131], v[18:19]
	v_rsq_f32_e32 v22, v16
	v_mul_f32_e32 v16, 0x45800000, v17
	v_mov_b32_dpp v21, v19 row_ror:4 row_mask:0xf bank_mask:0xf bound_ctrl:1
	v_mov_b32_dpp v20, v18 row_ror:4 row_mask:0xf bank_mask:0xf bound_ctrl:1
	v_pk_add_f32 v[18:19], v[18:19], v[20:21]
	v_cndmask_b32_e64 v16, v17, v16, s[0:1]
	v_mul_f32_e32 v17, 0x45800000, v22
	v_mov_b32_dpp v21, v19 row_ror:2 row_mask:0xf bank_mask:0xf bound_ctrl:1
	v_mov_b32_dpp v20, v18 row_ror:2 row_mask:0xf bank_mask:0xf bound_ctrl:1
	v_pk_add_f32 v[18:19], v[18:19], v[20:21]
	s_nop 1
	v_mov_b32_dpp v21, v19 row_ror:1 row_mask:0xf bank_mask:0xf bound_ctrl:1
	v_mov_b32_dpp v20, v18 row_ror:1 row_mask:0xf bank_mask:0xf bound_ctrl:1
	v_pk_add_f32 v[18:19], v[18:19], v[20:21]
	s_nop 0
	v_pk_fma_f32 v[18:19], v[18:19], s[24:25], v[132:133] op_sel_hi:[1,0,0]
	s_nop 0
	v_mul_f32_e32 v20, 0x4b800000, v19
	v_cmp_gt_f32_e64 s[0:1], s62, v19
	v_cmp_gt_f32_e64 s[4:5], s62, v18
	s_nop 0
	v_cndmask_b32_e64 v19, v19, v20, s[0:1]
	v_mul_f32_e32 v20, 0x4b800000, v18
	v_rsq_f32_e32 v19, v19
	v_cndmask_b32_e64 v18, v18, v20, s[4:5]
	v_rsq_f32_e32 v21, v18
	v_cndmask_b32_e64 v18, v22, v17, s[2:3]
	v_mul_f32_e32 v17, 0x45800000, v19
	v_cndmask_b32_e64 v20, v19, v17, s[0:1]
	v_mul_f32_e32 v17, 0x45800000, v21
	v_cndmask_b32_e64 v22, v21, v17, s[4:5]
	v_add_u32_e32 v17, 0xb0, v128
	v_pk_mul_f32 v[24:25], v[24:25], v[16:17] op_sel_hi:[1,0]
	v_mad_i64_i32 v[26:27], s[0:1], v17, s63, v[134:135]
	v_mul_f32_e32 v8, 0xbfb8aa3b, v25
	v_exp_f32_e32 v8, v8
	s_nop 0
	v_add_f32_e32 v8, 1.0, v8
	v_rcp_f32_e32 v17, v8
	v_mov_b32_e32 v8, v13
	v_pk_mul_f32 v[8:9], v[8:9], v[18:19] op_sel_hi:[1,0]
	v_mul_f32_e32 v17, v25, v17
	v_mul_f32_e32 v17, v24, v17
	v_mov_b32_e32 v24, v14
	v_mov_b32_e32 v25, v10
	v_pk_mul_f32 v[24:25], v[24:25], v[20:21] op_sel_hi:[1,0]
	v_mul_f32_e32 v13, 0xbfb8aa3b, v9
	v_mul_f32_e32 v10, 0xbfb8aa3b, v25
	v_exp_f32_e32 v14, v10
	v_mov_b32_e32 v10, v15
	v_exp_f32_e32 v19, v13
	v_pk_mul_f32 v[10:11], v[10:11], v[22:23] op_sel_hi:[1,0]
	v_add_f32_e32 v14, 1.0, v14
	v_mul_f32_e32 v15, 0xbfb8aa3b, v11
	v_exp_f32_e32 v15, v15
	v_add_f32_e32 v19, 1.0, v19
	v_rcp_f32_e32 v19, v19
	v_rcp_f32_e32 v14, v14
	v_add_f32_e32 v15, 1.0, v15
	v_rcp_f32_e32 v15, v15
	v_mul_f32_e32 v9, v9, v19
	v_mul_f32_e32 v8, v8, v9
	v_mul_f32_e32 v9, v25, v14
	v_mul_f32_e32 v14, v24, v9
	v_mul_f32_e32 v9, v11, v15
	v_mul_f32_e32 v15, v10, v9
	v_cndmask_b32_e32 v9, v17, v8, vcc
	v_mov_b32_e32 v11, v0
	v_mad_i64_i32 v[12:13], s[0:1], v12, s63, v[134:135]
	v_mov_b32_dpp v9, v9 quad_perm:[1,0,3,2] row_mask:0xf bank_mask:0xf bound_ctrl:1
	v_cndmask_b32_e32 v10, v9, v17, vcc
	v_cndmask_b32_e32 v8, v8, v9, vcc
	v_cvt_pk_bf16_f32 v10, v10, v8
	v_lshl_add_u64 v[8:9], v[26:27], 0, v[120:121]
	global_store_dword v[8:9], v10, off
	v_cndmask_b32_e32 v10, v14, v15, vcc
	v_lshl_add_u64 v[12:13], v[12:13], 0, v[120:121]
	s_nop 0
	v_mov_b32_dpp v17, v10 quad_perm:[1,0,3,2] row_mask:0xf bank_mask:0xf bound_ctrl:1
	v_mov_b32_e32 v10, v4
	v_pk_mul_f32 v[10:11], v[10:11], v[16:17] op_sel_hi:[1,0]
	v_cndmask_b32_e32 v14, v17, v14, vcc
	v_mul_f32_e32 v0, 0xbfb8aa3b, v11
	v_exp_f32_e32 v0, v0
	v_cndmask_b32_e32 v4, v15, v17, vcc
	v_cvt_pk_bf16_f32 v4, v14, v4
	global_store_dword v[12:13], v4, off
	v_add_f32_e32 v0, 1.0, v0
	v_rcp_f32_e32 v14, v0
	v_mov_b32_e32 v0, v5
	v_pk_mul_f32 v[0:1], v[0:1], v[18:19] op_sel_hi:[1,0]
	v_mul_f32_e32 v4, v11, v14
	v_mul_f32_e32 v5, 0xbfb8aa3b, v1
	v_exp_f32_e32 v5, v5
	v_mul_f32_e32 v10, v10, v4
	v_add_f32_e32 v4, 1.0, v5
	v_rcp_f32_e32 v11, v4
	v_mov_b32_e32 v4, v6
	v_mov_b32_e32 v5, v2
	v_pk_mul_f32 v[4:5], v[4:5], v[20:21] op_sel_hi:[1,0]
	v_mul_f32_e32 v1, v1, v11
	v_mul_f32_e32 v2, 0xbfb8aa3b, v5
	v_exp_f32_e32 v6, v2
	v_mov_b32_e32 v2, v7
	v_pk_mul_f32 v[2:3], v[2:3], v[22:23] op_sel_hi:[1,0]
	v_mul_f32_e32 v0, v0, v1
	v_mul_f32_e32 v7, 0xbfb8aa3b, v3
	v_exp_f32_e32 v7, v7
	v_add_f32_e32 v6, 1.0, v6
	v_rcp_f32_e32 v6, v6
	v_add_f32_e32 v7, 1.0, v7
	v_rcp_f32_e32 v7, v7
	v_mul_f32_e32 v1, v5, v6
	v_mul_f32_e32 v1, v4, v1
	v_mul_f32_e32 v3, v3, v7
	v_mul_f32_e32 v2, v2, v3
	v_cndmask_b32_e32 v3, v10, v0, vcc
	s_nop 1
	v_mov_b32_dpp v3, v3 quad_perm:[1,0,3,2] row_mask:0xf bank_mask:0xf bound_ctrl:1
	v_cndmask_b32_e32 v4, v3, v10, vcc
	v_cndmask_b32_e32 v0, v0, v3, vcc
	v_cvt_pk_bf16_f32 v0, v4, v0
	global_store_dword v[8:9], v0, off offset:32
	v_cndmask_b32_e32 v0, v1, v2, vcc
	s_nop 1
	v_mov_b32_dpp v0, v0 quad_perm:[1,0,3,2] row_mask:0xf bank_mask:0xf bound_ctrl:1
	v_cndmask_b32_e32 v1, v0, v1, vcc
	v_cndmask_b32_e32 v0, v2, v0, vcc
	v_cvt_pk_bf16_f32 v0, v1, v0
	global_store_dword v[12:13], v0, off offset:32
	s_waitcnt lgkmcnt(0)
	s_cmp_lg_u32 s64, 22
	s_mov_b32 s2, s30
	s_mov_b32 s0, s28
	s_mov_b32 s1, s64
	s_barrier
	s_cbranch_scc0 .LBB0_597

; template <class Epi>
; __device__ __forceinline__ void gemm_tile(const u16* __restrict__ A, const u16* __restrict__ Bt, int K,
;                                           int brow, int bcol, bool first, bool has_next, int nbrow, int nbcol, Epi epi) {
;     ...
;   if (has_next) {
;     STAGE(SB(0, 0), Bt, nbcol, 0); STAGE(SA(0, 0), A, nbrow, 0);
;     STAGE(SB(0, 1), Bt, nbcol + HALF, 0); STAGE(SA(0, 1), A, nbrow + HALF, 0);
;     STAGE(SB(1, 0), Bt, nbcol, 1); STAGE(SA(1, 0), A, nbrow, 1); STAGE(SB(1, 1), Bt, nbcol + HALF, 1);
;   }
.LBB0_595:
	s_or_b64 exec, exec, s[36:37]
	s_branch .LBB0_579
